# GEMM1/GEMM3 epilogues: per-row scale values staged into LDS by one extra DMA per tile, scale loads become ds_read (removes 8 serialized global round trips per pass)
# speedup vs baseline: 1.0465x; 1.0051x over previous
.Lg1a_hdr:
	s_cmp_ge_u32 s12, 672
	s_cbranch_scc1 .Lg1a_lastgrp
	s_mul_hi_u32 s0, s12, 0xc30c31
	s_mul_i32 s1, s0, 336
	s_sub_i32 s1, s12, s1
	s_lshr_b32 s6, s1, 4
	s_and_b32 s5, s1, 15
	s_lshl_b32 s0, s0, 4
	s_add_u32 s5, s0, s5
	s_branch .Lg1a_cont

.Lg1a_cont:
	s_lshl3_add_u32 s22, s5, s25
	s_lshl_b32 s23, s6, 1
	s_mul_i32 s0, s22, 0x40000
	s_add_u32 s14, s44, s0
	s_addc_u32 s15, s45, 0
	s_mul_i32 s0, s23, 0x40000
	s_add_u32 s16, s48, s0
	s_addc_u32 s17, s49, 0
	s_add_u32 s18, s16, 0x40000
	s_addc_u32 s19, s17, 0
	s_lshl_b32 s0, s22, 9
	s_add_u32 s30, s90, s0
	s_addc_u32 s31, s91, 0
	s_waitcnt vmcnt(0) lgkmcnt(0)
	s_barrier
	v_and_b32_e32 v166, 63, v148
	v_lshlrev_b32_e32 v166, 4, v166
	s_mov_b32 m0, 0xc400
	s_mov_b64 exec, 0xffffffff
	global_load_lds_dwordx4 v166, s[30:31]
	s_mov_b64 exec, -1
	s_add_u32 m0, s20, 0x0
	s_nop 0
	global_load_lds_dwordx4 v160, s[14:15]
	global_load_lds_dwordx4 v160, s[14:15] offset:1024
	s_add_u32 s14, s14, 0x2000
	s_addc_u32 s15, s15, 0
	s_add_u32 m0, s20, 0x2000
	s_nop 0
	global_load_lds_dwordx4 v160, s[16:17]
	global_load_lds_dwordx4 v160, s[16:17] offset:1024
	s_add_u32 s16, s16, 0x2000
	s_addc_u32 s17, s17, 0
	s_add_u32 m0, s20, 0x4000
	s_nop 0
	global_load_lds_dwordx4 v160, s[18:19]
	global_load_lds_dwordx4 v160, s[18:19] offset:1024
	s_add_u32 s18, s18, 0x2000
	s_addc_u32 s19, s19, 0
	s_waitcnt vmcnt(0)
	s_barrier
	s_add_u32 m0, s20, 0x6000
	s_nop 0
	global_load_lds_dwordx4 v160, s[14:15]
	global_load_lds_dwordx4 v160, s[14:15] offset:1024
	s_add_u32 s14, s14, 0x2000
	s_addc_u32 s15, s15, 0
	s_add_u32 m0, s20, 0x8000
	s_nop 0
	global_load_lds_dwordx4 v160, s[16:17]
	global_load_lds_dwordx4 v160, s[16:17] offset:1024
	s_add_u32 s16, s16, 0x2000
	s_addc_u32 s17, s17, 0
	s_add_u32 m0, s20, 0xa400
	s_nop 0
	global_load_lds_dwordx4 v160, s[18:19]
	global_load_lds_dwordx4 v160, s[18:19] offset:1024
	s_add_u32 s18, s18, 0x2000
	s_addc_u32 s19, s19, 0
	ds_read_b128 v[64:67], v154 offset:0
	ds_read_b128 v[72:75], v156 offset:8192
	ds_read_b128 v[76:79], v156 offset:10240
	ds_read_b128 v[80:83], v156 offset:16384
	ds_read_b128 v[150:153], v156 offset:18432
	ds_read_b128 v[68:71], v154 offset:2048
	s_waitcnt lgkmcnt(4)
	v_mfma_f32_32x32x16_bf16 v[48:63], v[64:67], v[72:75], 0
	s_waitcnt lgkmcnt(3)
	v_mfma_f32_32x32x16_bf16 v[32:47], v[64:67], v[76:79], 0
	s_waitcnt lgkmcnt(2)
	v_mfma_f32_32x32x16_bf16 v[132:147], v[64:67], v[80:83], 0
	s_waitcnt lgkmcnt(1)
	v_mfma_f32_32x32x16_bf16 v[116:131], v[64:67], v[150:153], 0
	ds_read_b128 v[64:67], v155 offset:0
	s_waitcnt lgkmcnt(1)
	v_mfma_f32_32x32x16_bf16 v[84:99], v[68:71], v[150:153], 0
	ds_read_b128 v[150:153], v157 offset:18432
	v_mfma_f32_32x32x16_bf16 v[100:115], v[68:71], v[80:83], 0
	ds_read_b128 v[80:83], v157 offset:16384
	v_mfma_f32_32x32x16_bf16 v[0:15], v[68:71], v[76:79], 0
	ds_read_b128 v[76:79], v157 offset:10240
	v_mfma_f32_32x32x16_bf16 v[16:31], v[68:71], v[72:75], 0
	ds_read_b128 v[72:75], v157 offset:8192
	ds_read_b128 v[68:71], v155 offset:2048
	s_waitcnt lgkmcnt(4)
	v_mfma_f32_32x32x16_bf16 v[116:131], v[64:67], v[150:153], v[116:131]
	s_waitcnt lgkmcnt(3)
	v_mfma_f32_32x32x16_bf16 v[132:147], v[64:67], v[80:83], v[132:147]
	s_waitcnt lgkmcnt(2)
	v_mfma_f32_32x32x16_bf16 v[32:47], v[64:67], v[76:79], v[32:47]
	s_waitcnt lgkmcnt(1)
	v_mfma_f32_32x32x16_bf16 v[48:63], v[64:67], v[72:75], v[48:63]
	s_waitcnt vmcnt(0) lgkmcnt(0)
	s_barrier
	ds_read_b128 v[64:67], v154 offset:24576
	s_add_u32 m0, s20, 0x0
	s_nop 0
	global_load_lds_dwordx4 v160, s[14:15]
	global_load_lds_dwordx4 v160, s[14:15] offset:1024
	s_add_u32 s14, s14, 0x2000
	s_addc_u32 s15, s15, 0
	v_mfma_f32_32x32x16_bf16 v[16:31], v[68:71], v[72:75], v[16:31]
	ds_read_b128 v[72:75], v156 offset:32768
	s_add_u32 m0, s20, 0x2000
	s_nop 0
	global_load_lds_dwordx4 v160, s[16:17]
	global_load_lds_dwordx4 v160, s[16:17] offset:1024
	s_add_u32 s16, s16, 0x2000
	s_addc_u32 s17, s17, 0
	v_mfma_f32_32x32x16_bf16 v[0:15], v[68:71], v[76:79], v[0:15]
	ds_read_b128 v[76:79], v156 offset:34816
	s_add_u32 m0, s20, 0x4000
	s_nop 0
	global_load_lds_dwordx4 v160, s[18:19]
	global_load_lds_dwordx4 v160, s[18:19] offset:1024
	s_add_u32 s18, s18, 0x2000
	s_addc_u32 s19, s19, 0
	v_mfma_f32_32x32x16_bf16 v[100:115], v[68:71], v[80:83], v[100:115]
	ds_read_b128 v[80:83], v156 offset:41984
	v_mfma_f32_32x32x16_bf16 v[84:99], v[68:71], v[150:153], v[84:99]
	ds_read_b128 v[150:153], v156 offset:44032
	ds_read_b128 v[68:71], v154 offset:26624
	s_waitcnt lgkmcnt(4)
	v_mfma_f32_32x32x16_bf16 v[48:63], v[64:67], v[72:75], v[48:63]
	s_waitcnt lgkmcnt(3)
	v_mfma_f32_32x32x16_bf16 v[32:47], v[64:67], v[76:79], v[32:47]
	s_waitcnt lgkmcnt(2)
	v_mfma_f32_32x32x16_bf16 v[132:147], v[64:67], v[80:83], v[132:147]
	s_waitcnt lgkmcnt(1)
	v_mfma_f32_32x32x16_bf16 v[116:131], v[64:67], v[150:153], v[116:131]
	ds_read_b128 v[64:67], v155 offset:24576
	s_waitcnt lgkmcnt(1)
	v_mfma_f32_32x32x16_bf16 v[84:99], v[68:71], v[150:153], v[84:99]
	ds_read_b128 v[150:153], v157 offset:44032
	v_mfma_f32_32x32x16_bf16 v[100:115], v[68:71], v[80:83], v[100:115]
	ds_read_b128 v[80:83], v157 offset:41984
	v_mfma_f32_32x32x16_bf16 v[0:15], v[68:71], v[76:79], v[0:15]
	ds_read_b128 v[76:79], v157 offset:34816
	v_mfma_f32_32x32x16_bf16 v[16:31], v[68:71], v[72:75], v[16:31]
	ds_read_b128 v[72:75], v157 offset:32768
	ds_read_b128 v[68:71], v155 offset:26624
	s_waitcnt lgkmcnt(4)
	v_mfma_f32_32x32x16_bf16 v[116:131], v[64:67], v[150:153], v[116:131]
	s_waitcnt lgkmcnt(3)
	v_mfma_f32_32x32x16_bf16 v[132:147], v[64:67], v[80:83], v[132:147]
	s_waitcnt lgkmcnt(2)
	v_mfma_f32_32x32x16_bf16 v[32:47], v[64:67], v[76:79], v[32:47]
	s_waitcnt lgkmcnt(1)
	v_mfma_f32_32x32x16_bf16 v[48:63], v[64:67], v[72:75], v[48:63]
	s_waitcnt vmcnt(0) lgkmcnt(0)
	s_barrier
	ds_read_b128 v[64:67], v154 offset:0
	s_add_u32 m0, s20, 0x6000
	s_nop 0
	global_load_lds_dwordx4 v160, s[14:15]
	global_load_lds_dwordx4 v160, s[14:15] offset:1024
	s_add_u32 s14, s14, 0x2000
	s_addc_u32 s15, s15, 0
	v_mfma_f32_32x32x16_bf16 v[16:31], v[68:71], v[72:75], v[16:31]
	ds_read_b128 v[72:75], v156 offset:8192
	s_add_u32 m0, s20, 0x8000
	s_nop 0
	global_load_lds_dwordx4 v160, s[16:17]
	global_load_lds_dwordx4 v160, s[16:17] offset:1024
	s_add_u32 s16, s16, 0x2000
	s_addc_u32 s17, s17, 0
	v_mfma_f32_32x32x16_bf16 v[0:15], v[68:71], v[76:79], v[0:15]
	ds_read_b128 v[76:79], v156 offset:10240
	s_add_u32 m0, s20, 0xa400
	s_nop 0
	global_load_lds_dwordx4 v160, s[18:19]
	global_load_lds_dwordx4 v160, s[18:19] offset:1024
	s_add_u32 s18, s18, 0x2000
	s_addc_u32 s19, s19, 0
	v_mfma_f32_32x32x16_bf16 v[100:115], v[68:71], v[80:83], v[100:115]
	ds_read_b128 v[80:83], v156 offset:16384
	v_mfma_f32_32x32x16_bf16 v[84:99], v[68:71], v[150:153], v[84:99]
	ds_read_b128 v[150:153], v156 offset:18432
	ds_read_b128 v[68:71], v154 offset:2048
	s_mov_b32 s21, 14

.Lg1a_epi:
	v_mov_b32_e32 v65, 0
	v_mov_b32_e32 v73, v148
	s_barrier
	s_movk_i32 s1, 0xffc0
	v_lshrrev_b32_e32 v74, 3, v73
	v_ashrrev_i32_e32 v64, 1, v73
	v_and_b32_e32 v74, 4, v74
	v_and_or_b32 v64, v64, s1, v74
	s_lshl_b32 s66, s4, 7
	v_add_u32_e32 v74, s66, v64
	v_ashrrev_i32_e32 v75, 31, v74
	v_lshl_add_u64 v[74:75], v[74:75], 2, s[90:91]
	v_subrev_u32_e32 v166, s30, v74
	ds_read_b128 v[80:83], v166 offset:50176
	v_and_b32_e32 v76, 0x5f, v73
	v_mul_lo_u32 v64, v64, s63
	v_lshl_add_u32 v64, v76, 1, v64
	s_lshl_b32 s4, s0, 7
	s_and_b32 s1, s0, -4
	s_mov_b64 s[6:7], -1
	s_cmp_lg_u32 s1, 4
	s_waitcnt lgkmcnt(0)
	v_mul_f32_e32 v32, v32, v80
	v_cvt_pk_bf16_f32 v32, v32, s0
	ds_write_b16 v64, v32 offset:64
	v_mul_f32_e32 v32, v49, v81
	v_cvt_pk_bf16_f32 v32, v32, s0
	ds_write_b16 v64, v32 offset:272
	v_mul_f32_e32 v32, v33, v81
	v_cvt_pk_bf16_f32 v32, v32, s0
	ds_write_b16 v64, v32 offset:336
	v_mul_f32_e32 v32, v50, v82
	v_cvt_pk_bf16_f32 v32, v32, s0
	ds_write_b16 v64, v32 offset:544
	v_mul_f32_e32 v32, v34, v82
	v_cvt_pk_bf16_f32 v32, v32, s0
	ds_write_b16 v64, v32 offset:608
	v_mul_f32_e32 v32, v51, v83
	v_cvt_pk_bf16_f32 v32, v32, s0
	ds_write_b16 v64, v32 offset:816
	v_mul_f32_e32 v32, v35, v83
	v_cvt_pk_bf16_f32 v32, v32, s0
	ds_write_b16 v64, v32 offset:880
	v_subrev_u32_e32 v166, s30, v74
	ds_read_b128 v[32:35], v166 offset:50208
	v_mul_f32_e32 v48, v48, v80
	v_cvt_pk_bf16_f32 v48, v48, s0
	ds_write_b16 v64, v48
	s_waitcnt lgkmcnt(0)
	v_mul_f32_e32 v48, v52, v32
	v_mul_f32_e32 v32, v36, v32
	v_cvt_pk_bf16_f32 v32, v32, s0
	ds_write_b16 v64, v32 offset:2240
	v_mul_f32_e32 v32, v53, v33
	v_cvt_pk_bf16_f32 v32, v32, s0
	ds_write_b16 v64, v32 offset:2448
	v_mul_f32_e32 v32, v37, v33
	v_cvt_pk_bf16_f32 v32, v32, s0
	ds_write_b16 v64, v32 offset:2512
	v_mul_f32_e32 v32, v54, v34
	v_cvt_pk_bf16_f32 v32, v32, s0
	ds_write_b16 v64, v32 offset:2720
	v_mul_f32_e32 v32, v38, v34
	v_cvt_pk_bf16_f32 v32, v32, s0
	ds_write_b16 v64, v32 offset:2784
	v_mul_f32_e32 v32, v55, v35
	v_cvt_pk_bf16_f32 v32, v32, s0
	ds_write_b16 v64, v32 offset:2992
	v_mul_f32_e32 v32, v39, v35
	v_cvt_pk_bf16_f32 v32, v32, s0
	ds_write_b16 v64, v32 offset:3056
	v_subrev_u32_e32 v166, s30, v74
	ds_read_b128 v[32:35], v166 offset:50240
	v_cvt_pk_bf16_f32 v48, v48, s0
	ds_write_b16 v64, v48 offset:2176
	s_waitcnt lgkmcnt(0)
	v_mul_f32_e32 v36, v56, v32
	v_mul_f32_e32 v32, v40, v32
	v_cvt_pk_bf16_f32 v32, v32, s0
	ds_write_b16 v64, v32 offset:4416
	v_mul_f32_e32 v32, v57, v33
	v_cvt_pk_bf16_f32 v32, v32, s0
	ds_write_b16 v64, v32 offset:4624
	v_mul_f32_e32 v32, v41, v33
	v_cvt_pk_bf16_f32 v32, v32, s0
	ds_write_b16 v64, v32 offset:4688
	v_mul_f32_e32 v32, v58, v34
	v_cvt_pk_bf16_f32 v32, v32, s0
	ds_write_b16 v64, v32 offset:4896
	v_mul_f32_e32 v32, v42, v34
	v_cvt_pk_bf16_f32 v32, v32, s0
	ds_write_b16 v64, v32 offset:4960
	v_mul_f32_e32 v32, v59, v35
	v_cvt_pk_bf16_f32 v32, v32, s0
	ds_write_b16 v64, v32 offset:5168
	v_mul_f32_e32 v32, v43, v35
	v_cvt_pk_bf16_f32 v32, v32, s0
	ds_write_b16 v64, v32 offset:5232
	v_subrev_u32_e32 v166, s30, v74
	ds_read_b128 v[32:35], v166 offset:50272
	v_cvt_pk_bf16_f32 v36, v36, s0
	ds_write_b16 v64, v36 offset:4352
	s_waitcnt lgkmcnt(0)
	v_mul_f32_e32 v36, v60, v32
	v_mul_f32_e32 v32, v44, v32
	v_cvt_pk_bf16_f32 v32, v32, s0
	ds_write_b16 v64, v32 offset:6592
	v_mul_f32_e32 v32, v61, v33
	v_cvt_pk_bf16_f32 v32, v32, s0
	ds_write_b16 v64, v32 offset:6800
	v_mul_f32_e32 v32, v45, v33
	v_cvt_pk_bf16_f32 v32, v32, s0
	ds_write_b16 v64, v32 offset:6864
	v_mul_f32_e32 v32, v62, v34
	v_cvt_pk_bf16_f32 v32, v32, s0
	ds_write_b16 v64, v32 offset:7072
	v_mul_f32_e32 v32, v46, v34
	v_cvt_pk_bf16_f32 v32, v32, s0
	ds_write_b16 v64, v32 offset:7136
	v_mul_f32_e32 v32, v63, v35
	v_cvt_pk_bf16_f32 v32, v32, s0
	ds_write_b16 v64, v32 offset:7344
	v_mul_f32_e32 v32, v47, v35
	v_cvt_pk_bf16_f32 v32, v32, s0
	ds_write_b16 v64, v32 offset:7408
	v_subrev_u32_e32 v166, s30, v74
	ds_read_b128 v[32:35], v166 offset:50304
	v_cvt_pk_bf16_f32 v36, v36, s0
	ds_write_b16 v64, v36 offset:6528
	s_waitcnt lgkmcnt(0)
	v_mul_f32_e32 v0, v0, v32
	v_cvt_pk_bf16_f32 v0, v0, s0
	ds_write_b16 v64, v0 offset:8768
	v_mul_f32_e32 v0, v17, v33
	v_cvt_pk_bf16_f32 v0, v0, s0
	ds_write_b16 v64, v0 offset:8976
	v_mul_f32_e32 v0, v1, v33
	v_cvt_pk_bf16_f32 v0, v0, s0
	ds_write_b16 v64, v0 offset:9040
	v_mul_f32_e32 v0, v18, v34
	v_cvt_pk_bf16_f32 v0, v0, s0
	ds_write_b16 v64, v0 offset:9248
	v_mul_f32_e32 v0, v2, v34
	v_cvt_pk_bf16_f32 v0, v0, s0
	ds_write_b16 v64, v0 offset:9312
	v_mul_f32_e32 v0, v19, v35
	v_cvt_pk_bf16_f32 v0, v0, s0
	ds_write_b16 v64, v0 offset:9520
	v_mul_f32_e32 v0, v3, v35
	v_cvt_pk_bf16_f32 v0, v0, s0
	ds_write_b16 v64, v0 offset:9584
	v_subrev_u32_e32 v166, s30, v74
	ds_read_b128 v[0:3], v166 offset:50336
	v_mul_f32_e32 v16, v16, v32
	v_cvt_pk_bf16_f32 v16, v16, s0
	ds_write_b16 v64, v16 offset:8704
	s_waitcnt lgkmcnt(0)
	v_mul_f32_e32 v16, v20, v0
	v_mul_f32_e32 v0, v4, v0
	v_cvt_pk_bf16_f32 v0, v0, s0
	ds_write_b16 v64, v0 offset:10944
	v_mul_f32_e32 v0, v21, v1
	v_cvt_pk_bf16_f32 v0, v0, s0
	ds_write_b16 v64, v0 offset:11152
	v_mul_f32_e32 v0, v5, v1
	v_cvt_pk_bf16_f32 v0, v0, s0
	ds_write_b16 v64, v0 offset:11216
	v_mul_f32_e32 v0, v22, v2
	v_cvt_pk_bf16_f32 v0, v0, s0
	ds_write_b16 v64, v0 offset:11424
	v_mul_f32_e32 v0, v6, v2
	v_cvt_pk_bf16_f32 v0, v0, s0
	ds_write_b16 v64, v0 offset:11488
	v_mul_f32_e32 v0, v23, v3
	v_cvt_pk_bf16_f32 v0, v0, s0
	ds_write_b16 v64, v0 offset:11696
	v_mul_f32_e32 v0, v7, v3
	v_cvt_pk_bf16_f32 v0, v0, s0
	ds_write_b16 v64, v0 offset:11760
	v_subrev_u32_e32 v166, s30, v74
	ds_read_b128 v[0:3], v166 offset:50368
	v_cvt_pk_bf16_f32 v16, v16, s0
	ds_write_b16 v64, v16 offset:10880
	s_waitcnt lgkmcnt(0)
	v_mul_f32_e32 v4, v24, v0
	v_mul_f32_e32 v0, v8, v0
	v_cvt_pk_bf16_f32 v0, v0, s0
	ds_write_b16 v64, v0 offset:13120
	v_mul_f32_e32 v0, v25, v1
	v_cvt_pk_bf16_f32 v0, v0, s0
	ds_write_b16 v64, v0 offset:13328
	v_mul_f32_e32 v0, v9, v1
	v_cvt_pk_bf16_f32 v0, v0, s0
	ds_write_b16 v64, v0 offset:13392
	v_mul_f32_e32 v0, v26, v2
	v_cvt_pk_bf16_f32 v0, v0, s0
	ds_write_b16 v64, v0 offset:13600
	v_mul_f32_e32 v0, v10, v2
	v_cvt_pk_bf16_f32 v0, v0, s0
	ds_write_b16 v64, v0 offset:13664
	v_mul_f32_e32 v0, v27, v3
	v_cvt_pk_bf16_f32 v0, v0, s0
	ds_write_b16 v64, v0 offset:13872
	v_mul_f32_e32 v0, v11, v3
	v_cvt_pk_bf16_f32 v0, v0, s0
	ds_write_b16 v64, v0 offset:13936
	v_subrev_u32_e32 v166, s30, v74
	ds_read_b128 v[0:3], v166 offset:50400
	v_cvt_pk_bf16_f32 v4, v4, s0
	ds_write_b16 v64, v4 offset:13056
	s_waitcnt lgkmcnt(0)
	v_mul_f32_e32 v4, v28, v0
	v_mul_f32_e32 v0, v12, v0
	v_cvt_pk_bf16_f32 v0, v0, s0
	ds_write_b16 v64, v0 offset:15296
	v_mul_f32_e32 v0, v29, v1
	v_cvt_pk_bf16_f32 v0, v0, s0
	ds_write_b16 v64, v0 offset:15504
	v_mul_f32_e32 v0, v13, v1
	v_cvt_pk_bf16_f32 v0, v0, s0
	ds_write_b16 v64, v0 offset:15568
	v_mul_f32_e32 v0, v30, v2
	v_cvt_pk_bf16_f32 v0, v0, s0
	ds_write_b16 v64, v0 offset:15776
	v_mul_f32_e32 v0, v14, v2
	v_cvt_pk_bf16_f32 v0, v0, s0
	ds_write_b16 v64, v0 offset:15840
	v_mul_f32_e32 v0, v31, v3
	v_cvt_pk_bf16_f32 v0, v0, s0
	ds_write_b16 v64, v0 offset:16048
	v_mul_f32_e32 v0, v15, v3
	v_cvt_pk_bf16_f32 v4, v4, s0
	v_cvt_pk_bf16_f32 v0, v0, s0
	ds_write_b16 v64, v4 offset:15232
	ds_write_b16 v64, v0 offset:16112
	s_waitcnt lgkmcnt(0)
	s_barrier
	s_cbranch_scc0 .LBB0_121
	s_sub_i32 s1, s0, 20
	s_add_i32 s2, s4, 0xfffff800
	s_cmp_lt_u32 s1, 10
	s_cselect_b32 s2, s2, -1
	s_mov_b64 s[6:7], 0

.Lg2a_hdr:
	s_cmp_ge_u32 s4, 128
	s_cbranch_scc1 .Lg2a_lastgrp
	s_mul_hi_u32 s2, s4, 0x4000000
	s_mul_i32 s3, s2, 64
	s_sub_i32 s3, s4, s3
	s_lshr_b32 s11, s3, 4
	s_and_b32 s7, s3, 15
	s_lshl_b32 s2, s2, 4
	s_add_u32 s7, s2, s7
	s_branch .Lg2a_cont

.Lg3a_hdr:
	s_cmp_ge_u32 s2, 704
	s_cbranch_scc1 .Lg3a_lastgrp
	s_mul_hi_u32 s8, s2, 0xba2e8c
	s_mul_i32 s9, s8, 352
	s_sub_i32 s9, s2, s9
	s_lshr_b32 s13, s9, 4
	s_and_b32 s12, s9, 15
	s_lshl_b32 s8, s8, 4
	s_add_u32 s12, s8, s12
	s_branch .Lg3a_cont

.Lg3a_cont:
	s_lshl3_add_u32 s22, s12, s25
	s_lshl_b32 s23, s13, 1
	s_mul_i32 s8, s22, 0x40000
	s_add_u32 s14, s44, s8
	s_addc_u32 s15, s45, 0
	s_mul_i32 s8, s23, 0x40000
	s_add_u32 s8, s8, 0xd80000
	s_add_u32 s16, s48, s8
	s_addc_u32 s17, s49, 0
	s_add_u32 s18, s16, 0x40000
	s_addc_u32 s19, s17, 0
	s_lshl_b32 s8, s22, 9
	s_add_u32 s30, s4, s8
	s_addc_u32 s31, s5, 0
	s_waitcnt vmcnt(0) lgkmcnt(0)
	s_barrier
	v_and_b32_e32 v167, 63, v148
	v_lshlrev_b32_e32 v167, 4, v167
	s_mov_b32 m0, 0xc400
	s_mov_b64 exec, 0xffffffff
	global_load_lds_dwordx4 v167, s[30:31]
	s_mov_b64 exec, -1
	s_add_u32 m0, s20, 0x0
	s_nop 0
	global_load_lds_dwordx4 v164, s[14:15]
	global_load_lds_dwordx4 v164, s[14:15] offset:1024
	s_add_u32 s14, s14, 0x2000
	s_addc_u32 s15, s15, 0
	s_add_u32 m0, s20, 0x2000
	s_nop 0
	global_load_lds_dwordx4 v164, s[16:17]
	global_load_lds_dwordx4 v164, s[16:17] offset:1024
	s_add_u32 s16, s16, 0x2000
	s_addc_u32 s17, s17, 0
	s_add_u32 m0, s20, 0x4000
	s_nop 0
	global_load_lds_dwordx4 v164, s[18:19]
	global_load_lds_dwordx4 v164, s[18:19] offset:1024
	s_add_u32 s18, s18, 0x2000
	s_addc_u32 s19, s19, 0
	s_waitcnt vmcnt(0)
	s_barrier
	s_add_u32 m0, s20, 0x6000
	s_nop 0
	global_load_lds_dwordx4 v164, s[14:15]
	global_load_lds_dwordx4 v164, s[14:15] offset:1024
	s_add_u32 s14, s14, 0x2000
	s_addc_u32 s15, s15, 0
	s_add_u32 m0, s20, 0x8000
	s_nop 0
	global_load_lds_dwordx4 v164, s[16:17]
	global_load_lds_dwordx4 v164, s[16:17] offset:1024
	s_add_u32 s16, s16, 0x2000
	s_addc_u32 s17, s17, 0
	s_add_u32 m0, s20, 0xa400
	s_nop 0
	global_load_lds_dwordx4 v164, s[18:19]
	global_load_lds_dwordx4 v164, s[18:19] offset:1024
	s_add_u32 s18, s18, 0x2000
	s_addc_u32 s19, s19, 0
	ds_read_b128 v[82:85], v160 offset:0
	ds_read_b128 v[138:141], v162 offset:8192
	ds_read_b128 v[142:145], v162 offset:10240
	ds_read_b128 v[150:153], v162 offset:16384
	ds_read_b128 v[154:157], v162 offset:18432
	ds_read_b128 v[134:137], v160 offset:2048
	s_waitcnt lgkmcnt(4)
	v_mfma_f32_32x32x16_bf16 v[32:47], v[82:85], v[138:141], 0
	s_waitcnt lgkmcnt(3)
	v_mfma_f32_32x32x16_bf16 v[48:63], v[82:85], v[142:145], 0
	s_waitcnt lgkmcnt(2)
	v_mfma_f32_32x32x16_bf16 v[86:101], v[82:85], v[150:153], 0
	s_waitcnt lgkmcnt(1)
	v_mfma_f32_32x32x16_bf16 v[102:117], v[82:85], v[154:157], 0
	ds_read_b128 v[82:85], v161 offset:0
	s_waitcnt lgkmcnt(1)
	v_mfma_f32_32x32x16_bf16 v[66:81], v[134:137], v[154:157], 0
	ds_read_b128 v[154:157], v163 offset:18432
	v_mfma_f32_32x32x16_bf16 v[118:133], v[134:137], v[150:153], 0
	ds_read_b128 v[150:153], v163 offset:16384
	v_mfma_f32_32x32x16_bf16 v[16:31], v[134:137], v[142:145], 0
	ds_read_b128 v[142:145], v163 offset:10240
	v_mfma_f32_32x32x16_bf16 v[0:15], v[134:137], v[138:141], 0
	ds_read_b128 v[138:141], v163 offset:8192
	ds_read_b128 v[134:137], v161 offset:2048
	s_waitcnt lgkmcnt(4)
	v_mfma_f32_32x32x16_bf16 v[102:117], v[82:85], v[154:157], v[102:117]
	s_waitcnt lgkmcnt(3)
	v_mfma_f32_32x32x16_bf16 v[86:101], v[82:85], v[150:153], v[86:101]
	s_waitcnt lgkmcnt(2)
	v_mfma_f32_32x32x16_bf16 v[48:63], v[82:85], v[142:145], v[48:63]
	s_waitcnt lgkmcnt(1)
	v_mfma_f32_32x32x16_bf16 v[32:47], v[82:85], v[138:141], v[32:47]
	s_waitcnt vmcnt(0) lgkmcnt(0)
	s_barrier
	ds_read_b128 v[82:85], v160 offset:24576
	s_add_u32 m0, s20, 0x0
	s_nop 0
	global_load_lds_dwordx4 v164, s[14:15]
	global_load_lds_dwordx4 v164, s[14:15] offset:1024
	s_add_u32 s14, s14, 0x2000
	s_addc_u32 s15, s15, 0
	v_mfma_f32_32x32x16_bf16 v[0:15], v[134:137], v[138:141], v[0:15]
	ds_read_b128 v[138:141], v162 offset:32768
	s_add_u32 m0, s20, 0x2000
	s_nop 0
	global_load_lds_dwordx4 v164, s[16:17]
	global_load_lds_dwordx4 v164, s[16:17] offset:1024
	s_add_u32 s16, s16, 0x2000
	s_addc_u32 s17, s17, 0
	v_mfma_f32_32x32x16_bf16 v[16:31], v[134:137], v[142:145], v[16:31]
	ds_read_b128 v[142:145], v162 offset:34816
	s_add_u32 m0, s20, 0x4000
	s_nop 0
	global_load_lds_dwordx4 v164, s[18:19]
	global_load_lds_dwordx4 v164, s[18:19] offset:1024
	s_add_u32 s18, s18, 0x2000
	s_addc_u32 s19, s19, 0
	v_mfma_f32_32x32x16_bf16 v[118:133], v[134:137], v[150:153], v[118:133]
	ds_read_b128 v[150:153], v162 offset:41984
	v_mfma_f32_32x32x16_bf16 v[66:81], v[134:137], v[154:157], v[66:81]
	ds_read_b128 v[154:157], v162 offset:44032
	ds_read_b128 v[134:137], v160 offset:26624
	s_waitcnt lgkmcnt(4)
	v_mfma_f32_32x32x16_bf16 v[32:47], v[82:85], v[138:141], v[32:47]
	s_waitcnt lgkmcnt(3)
	v_mfma_f32_32x32x16_bf16 v[48:63], v[82:85], v[142:145], v[48:63]
	s_waitcnt lgkmcnt(2)
	v_mfma_f32_32x32x16_bf16 v[86:101], v[82:85], v[150:153], v[86:101]
	s_waitcnt lgkmcnt(1)
	v_mfma_f32_32x32x16_bf16 v[102:117], v[82:85], v[154:157], v[102:117]
	ds_read_b128 v[82:85], v161 offset:24576
	s_waitcnt lgkmcnt(1)
	v_mfma_f32_32x32x16_bf16 v[66:81], v[134:137], v[154:157], v[66:81]
	ds_read_b128 v[154:157], v163 offset:44032
	v_mfma_f32_32x32x16_bf16 v[118:133], v[134:137], v[150:153], v[118:133]
	ds_read_b128 v[150:153], v163 offset:41984
	v_mfma_f32_32x32x16_bf16 v[16:31], v[134:137], v[142:145], v[16:31]
	ds_read_b128 v[142:145], v163 offset:34816
	v_mfma_f32_32x32x16_bf16 v[0:15], v[134:137], v[138:141], v[0:15]
	ds_read_b128 v[138:141], v163 offset:32768
	ds_read_b128 v[134:137], v161 offset:26624
	s_waitcnt lgkmcnt(4)
	v_mfma_f32_32x32x16_bf16 v[102:117], v[82:85], v[154:157], v[102:117]
	s_waitcnt lgkmcnt(3)
	v_mfma_f32_32x32x16_bf16 v[86:101], v[82:85], v[150:153], v[86:101]
	s_waitcnt lgkmcnt(2)
	v_mfma_f32_32x32x16_bf16 v[48:63], v[82:85], v[142:145], v[48:63]
	s_waitcnt lgkmcnt(1)
	v_mfma_f32_32x32x16_bf16 v[32:47], v[82:85], v[138:141], v[32:47]
	s_waitcnt vmcnt(0) lgkmcnt(0)
	s_barrier
	ds_read_b128 v[82:85], v160 offset:0
	s_add_u32 m0, s20, 0x6000
	s_nop 0
	global_load_lds_dwordx4 v164, s[14:15]
	global_load_lds_dwordx4 v164, s[14:15] offset:1024
	s_add_u32 s14, s14, 0x2000
	s_addc_u32 s15, s15, 0
	v_mfma_f32_32x32x16_bf16 v[0:15], v[134:137], v[138:141], v[0:15]
	ds_read_b128 v[138:141], v162 offset:8192
	s_add_u32 m0, s20, 0x8000
	s_nop 0
	global_load_lds_dwordx4 v164, s[16:17]
	global_load_lds_dwordx4 v164, s[16:17] offset:1024
	s_add_u32 s16, s16, 0x2000
	s_addc_u32 s17, s17, 0
	v_mfma_f32_32x32x16_bf16 v[16:31], v[134:137], v[142:145], v[16:31]
	ds_read_b128 v[142:145], v162 offset:10240
	s_add_u32 m0, s20, 0xa400
	s_nop 0
	global_load_lds_dwordx4 v164, s[18:19]
	global_load_lds_dwordx4 v164, s[18:19] offset:1024
	s_add_u32 s18, s18, 0x2000
	s_addc_u32 s19, s19, 0
	v_mfma_f32_32x32x16_bf16 v[118:133], v[134:137], v[150:153], v[118:133]
	ds_read_b128 v[150:153], v162 offset:16384
	v_mfma_f32_32x32x16_bf16 v[66:81], v[134:137], v[154:157], v[66:81]
	ds_read_b128 v[154:157], v162 offset:18432
	ds_read_b128 v[134:137], v160 offset:2048
	s_mov_b32 s21, 14

.Lg3a_epi:
	v_mov_b32_e32 v65, 0
	v_mov_b32_e32 v73, v148
	v_mov_b32_e32 v74, 0x358637bd
	v_mov_b32_e32 v75, 0
	s_barrier
	s_movk_i32 s1, 0xffc0
	v_lshrrev_b32_e32 v76, 3, v73
	v_ashrrev_i32_e32 v64, 1, v73
	v_and_b32_e32 v76, 4, v76
	v_and_or_b32 v76, v64, s1, v76
	s_lshl_b32 s11, s0, 7
	v_add_u32_e32 v78, s11, v76
	v_ashrrev_i32_e32 v79, 31, v78
	v_lshl_add_u64 v[82:83], v[78:79], 2, s[4:5]
	v_subrev_u32_e32 v167, s30, v82
	ds_read_b128 v[82:85], v167 offset:50176
	v_and_b32_e32 v64, 31, v73
	v_lshlrev_b32_e32 v64, 1, v64
	v_and_or_b32 v64, v73, 64, v64
	v_mad_u64_u32 v[76:77], s[0:1], v76, s59, v[64:65]
	s_waitcnt lgkmcnt(0)
	v_pk_fma_f32 v[82:83], v[82:83], s[6:7], v[74:75] op_sel_hi:[1,0,0]
	s_nop 0
	v_mul_f32_e32 v64, 0x4b800000, v82
	v_cmp_gt_f32_e64 s[0:1], s60, v82
	v_cmp_gt_f32_e32 vcc, s60, v83
	s_nop 0
	v_cndmask_b32_e64 v64, v82, v64, s[0:1]
	v_rsq_f32_e32 v64, v64
	s_nop 0
	v_mul_f32_e32 v77, 0x45800000, v64
	v_cndmask_b32_e64 v64, v64, v77, s[0:1]
	v_mul_f32_e32 v32, v32, v64
	v_mul_f32_e32 v48, v48, v64
	v_mul_f32_e32 v64, 0xbfb8aa3b, v32
	v_exp_f32_e32 v64, v64
	s_nop 0
	v_add_f32_e32 v64, 1.0, v64
	v_rcp_f32_e32 v64, v64
	s_nop 0
	v_mul_f32_e32 v32, v32, v64
	v_mul_f32_e32 v32, v48, v32
	v_cvt_pk_bf16_f32 v32, v32, s0
	ds_write_b16 v76, v32
	v_mul_f32_e32 v32, 0x4b800000, v83
	v_cndmask_b32_e32 v32, v83, v32, vcc
	v_rsq_f32_e32 v32, v32
	s_nop 0
	v_mul_f32_e32 v48, 0x45800000, v32
	v_cndmask_b32_e32 v32, v32, v48, vcc
	v_mul_f32_e32 v33, v33, v32
	v_mul_f32_e32 v48, 0xbfb8aa3b, v33
	v_exp_f32_e32 v48, v48
	v_mul_f32_e32 v32, v49, v32
	v_add_f32_e32 v48, 1.0, v48
	v_rcp_f32_e32 v48, v48
	s_nop 0
	v_mul_f32_e32 v33, v33, v48
	v_mul_f32_e32 v32, v32, v33
	v_cvt_pk_bf16_f32 v32, v32, s0
	ds_write_b16 v76, v32 offset:144
	v_pk_fma_f32 v[32:33], v[84:85], s[6:7], v[74:75] op_sel_hi:[1,0,0]
	s_nop 0
	v_mul_f32_e32 v48, 0x4b800000, v32
	v_cmp_gt_f32_e64 s[0:1], s60, v32
	v_cmp_gt_f32_e32 vcc, s60, v33
	s_nop 0
	v_cndmask_b32_e64 v32, v32, v48, s[0:1]
	v_rsq_f32_e32 v32, v32
	s_nop 0
	v_mul_f32_e32 v48, 0x45800000, v32
	v_cndmask_b32_e64 v32, v32, v48, s[0:1]
	v_mul_f32_e32 v34, v34, v32
	v_mul_f32_e32 v48, 0xbfb8aa3b, v34
	v_exp_f32_e32 v48, v48
	v_mul_f32_e32 v32, v50, v32
	v_add_f32_e32 v48, 1.0, v48
	v_rcp_f32_e32 v48, v48
	s_nop 0
	v_mul_f32_e32 v34, v34, v48
	v_mul_f32_e32 v32, v32, v34
	v_cvt_pk_bf16_f32 v32, v32, s0
	ds_write_b16 v76, v32 offset:288
	v_mul_f32_e32 v32, 0x4b800000, v33
	v_cndmask_b32_e32 v32, v33, v32, vcc
	v_rsq_f32_e32 v32, v32
	s_nop 0
	v_mul_f32_e32 v33, 0x45800000, v32
	v_cndmask_b32_e32 v32, v32, v33, vcc
	v_mul_f32_e32 v33, v35, v32
	v_mul_f32_e32 v34, 0xbfb8aa3b, v33
	v_exp_f32_e32 v34, v34
	v_mul_f32_e32 v32, v51, v32
	v_add_f32_e32 v34, 1.0, v34
	v_rcp_f32_e32 v34, v34
	s_nop 0
	v_mul_f32_e32 v33, v33, v34
	v_mul_f32_e32 v32, v32, v33
	v_cvt_pk_bf16_f32 v32, v32, s0
	ds_write_b16 v76, v32 offset:432
	v_or_b32_e32 v32, 8, v78
	v_ashrrev_i32_e32 v33, 31, v32
	v_lshl_add_u64 v[32:33], v[32:33], 2, s[4:5]
	v_subrev_u32_e32 v167, s30, v32
	ds_read_b128 v[32:35], v167 offset:50176
	s_waitcnt lgkmcnt(0)
	v_pk_fma_f32 v[32:33], v[32:33], s[6:7], v[74:75] op_sel_hi:[1,0,0]
	s_nop 0
	v_mul_f32_e32 v48, 0x4b800000, v32
	v_cmp_gt_f32_e64 s[0:1], s60, v32
	v_cmp_gt_f32_e32 vcc, s60, v33
	s_nop 0
	v_cndmask_b32_e64 v32, v32, v48, s[0:1]
	v_rsq_f32_e32 v32, v32
	s_nop 0
	v_mul_f32_e32 v48, 0x45800000, v32
	v_cndmask_b32_e64 v32, v32, v48, s[0:1]
	v_mul_f32_e32 v36, v36, v32
	v_mul_f32_e32 v48, 0xbfb8aa3b, v36
	v_exp_f32_e32 v48, v48
	v_mul_f32_e32 v32, v52, v32
	v_add_f32_e32 v48, 1.0, v48
	v_rcp_f32_e32 v48, v48
	s_nop 0
	v_mul_f32_e32 v36, v36, v48
	v_mul_f32_e32 v32, v32, v36
	v_cvt_pk_bf16_f32 v32, v32, s0
	ds_write_b16 v76, v32 offset:1152
	v_mul_f32_e32 v32, 0x4b800000, v33
	v_cndmask_b32_e32 v32, v33, v32, vcc
	v_rsq_f32_e32 v32, v32
	s_nop 0
	v_mul_f32_e32 v33, 0x45800000, v32
	v_cndmask_b32_e32 v32, v32, v33, vcc
	v_mul_f32_e32 v33, v37, v32
	v_mul_f32_e32 v36, 0xbfb8aa3b, v33
	v_exp_f32_e32 v36, v36
	v_mul_f32_e32 v32, v53, v32
	v_add_f32_e32 v36, 1.0, v36
	v_rcp_f32_e32 v36, v36
	s_nop 0
	v_mul_f32_e32 v33, v33, v36
	v_mul_f32_e32 v32, v32, v33
	v_cvt_pk_bf16_f32 v32, v32, s0
	ds_write_b16 v76, v32 offset:1296
	v_pk_fma_f32 v[32:33], v[34:35], s[6:7], v[74:75] op_sel_hi:[1,0,0]
	s_nop 0
	v_mul_f32_e32 v34, 0x4b800000, v32
	v_cmp_gt_f32_e64 s[0:1], s60, v32
	v_cmp_gt_f32_e32 vcc, s60, v33
	s_nop 0
	v_cndmask_b32_e64 v32, v32, v34, s[0:1]
	v_rsq_f32_e32 v32, v32
	s_nop 0
	v_mul_f32_e32 v34, 0x45800000, v32
	v_cndmask_b32_e64 v32, v32, v34, s[0:1]
	v_mul_f32_e32 v34, v38, v32
	v_mul_f32_e32 v35, 0xbfb8aa3b, v34
	v_exp_f32_e32 v35, v35
	v_mul_f32_e32 v32, v54, v32
	v_add_f32_e32 v35, 1.0, v35
	v_rcp_f32_e32 v35, v35
	s_nop 0
	v_mul_f32_e32 v34, v34, v35
	v_mul_f32_e32 v32, v32, v34
	v_cvt_pk_bf16_f32 v32, v32, s0
	ds_write_b16 v76, v32 offset:1440
	v_mul_f32_e32 v32, 0x4b800000, v33
	v_cndmask_b32_e32 v32, v33, v32, vcc
	v_rsq_f32_e32 v32, v32
	s_nop 0
	v_mul_f32_e32 v33, 0x45800000, v32
	v_cndmask_b32_e32 v32, v32, v33, vcc
	v_mul_f32_e32 v33, v39, v32
	v_mul_f32_e32 v34, 0xbfb8aa3b, v33
	v_exp_f32_e32 v34, v34
	v_mul_f32_e32 v32, v55, v32
	v_add_f32_e32 v34, 1.0, v34
	v_rcp_f32_e32 v34, v34
	s_nop 0
	v_mul_f32_e32 v33, v33, v34
	v_mul_f32_e32 v32, v32, v33
	v_cvt_pk_bf16_f32 v32, v32, s0
	ds_write_b16 v76, v32 offset:1584
	v_or_b32_e32 v32, 16, v78
	v_ashrrev_i32_e32 v33, 31, v32
	v_lshl_add_u64 v[32:33], v[32:33], 2, s[4:5]
	v_subrev_u32_e32 v167, s30, v32
	ds_read_b128 v[32:35], v167 offset:50176
	s_waitcnt lgkmcnt(0)
	v_pk_fma_f32 v[32:33], v[32:33], s[6:7], v[74:75] op_sel_hi:[1,0,0]
	s_nop 0
	v_mul_f32_e32 v36, 0x4b800000, v32
	v_cmp_gt_f32_e64 s[0:1], s60, v32
	v_cmp_gt_f32_e32 vcc, s60, v33
	s_nop 0
	v_cndmask_b32_e64 v32, v32, v36, s[0:1]
	v_rsq_f32_e32 v32, v32
	s_nop 0
	v_mul_f32_e32 v36, 0x45800000, v32
	v_cndmask_b32_e64 v32, v32, v36, s[0:1]
	v_mul_f32_e32 v36, v40, v32
	v_mul_f32_e32 v37, 0xbfb8aa3b, v36
	v_exp_f32_e32 v37, v37
	v_mul_f32_e32 v32, v56, v32
	v_add_f32_e32 v37, 1.0, v37
	v_rcp_f32_e32 v37, v37
	s_nop 0
	v_mul_f32_e32 v36, v36, v37
	v_mul_f32_e32 v32, v32, v36
	v_cvt_pk_bf16_f32 v32, v32, s0
	ds_write_b16 v76, v32 offset:2304
	v_mul_f32_e32 v32, 0x4b800000, v33
	v_cndmask_b32_e32 v32, v33, v32, vcc
	v_rsq_f32_e32 v32, v32
	s_nop 0
	v_mul_f32_e32 v33, 0x45800000, v32
	v_cndmask_b32_e32 v32, v32, v33, vcc
	v_mul_f32_e32 v33, v41, v32
	v_mul_f32_e32 v36, 0xbfb8aa3b, v33
	v_exp_f32_e32 v36, v36
	v_mul_f32_e32 v32, v57, v32
	v_add_f32_e32 v36, 1.0, v36
	v_rcp_f32_e32 v36, v36
	s_nop 0
	v_mul_f32_e32 v33, v33, v36
	v_mul_f32_e32 v32, v32, v33
	v_cvt_pk_bf16_f32 v32, v32, s0
	ds_write_b16 v76, v32 offset:2448
	v_pk_fma_f32 v[32:33], v[34:35], s[6:7], v[74:75] op_sel_hi:[1,0,0]
	s_nop 0
	v_mul_f32_e32 v34, 0x4b800000, v32
	v_cmp_gt_f32_e64 s[0:1], s60, v32
	v_cmp_gt_f32_e32 vcc, s60, v33
	s_nop 0
	v_cndmask_b32_e64 v32, v32, v34, s[0:1]
	v_rsq_f32_e32 v32, v32
	s_nop 0
	v_mul_f32_e32 v34, 0x45800000, v32
	v_cndmask_b32_e64 v32, v32, v34, s[0:1]
	v_mul_f32_e32 v34, v42, v32
	v_mul_f32_e32 v35, 0xbfb8aa3b, v34
	v_exp_f32_e32 v35, v35
	v_mul_f32_e32 v32, v58, v32
	v_add_f32_e32 v35, 1.0, v35
	v_rcp_f32_e32 v35, v35
	s_nop 0
	v_mul_f32_e32 v34, v34, v35
	v_mul_f32_e32 v32, v32, v34
	v_cvt_pk_bf16_f32 v32, v32, s0
	ds_write_b16 v76, v32 offset:2592
	v_mul_f32_e32 v32, 0x4b800000, v33
	v_cndmask_b32_e32 v32, v33, v32, vcc
	v_rsq_f32_e32 v32, v32
	s_nop 0
	v_mul_f32_e32 v33, 0x45800000, v32
	v_cndmask_b32_e32 v32, v32, v33, vcc
	v_mul_f32_e32 v33, v43, v32
	v_mul_f32_e32 v34, 0xbfb8aa3b, v33
	v_exp_f32_e32 v34, v34
	v_mul_f32_e32 v32, v59, v32
	v_add_f32_e32 v34, 1.0, v34
	v_rcp_f32_e32 v34, v34
	s_nop 0
	v_mul_f32_e32 v33, v33, v34
	v_mul_f32_e32 v32, v32, v33
	v_cvt_pk_bf16_f32 v32, v32, s0
	ds_write_b16 v76, v32 offset:2736
	v_or_b32_e32 v32, 24, v78
	v_ashrrev_i32_e32 v33, 31, v32
	v_lshl_add_u64 v[32:33], v[32:33], 2, s[4:5]
	v_subrev_u32_e32 v167, s30, v32
	ds_read_b128 v[32:35], v167 offset:50176
	s_waitcnt lgkmcnt(0)
	v_pk_fma_f32 v[32:33], v[32:33], s[6:7], v[74:75] op_sel_hi:[1,0,0]
	s_nop 0
	v_mul_f32_e32 v36, 0x4b800000, v32
	v_cmp_gt_f32_e64 s[0:1], s60, v32
	v_cmp_gt_f32_e32 vcc, s60, v33
	s_nop 0
	v_cndmask_b32_e64 v32, v32, v36, s[0:1]
	v_rsq_f32_e32 v32, v32
	s_nop 0
	v_mul_f32_e32 v36, 0x45800000, v32
	v_cndmask_b32_e64 v32, v32, v36, s[0:1]
	v_mul_f32_e32 v36, v44, v32
	v_mul_f32_e32 v37, 0xbfb8aa3b, v36
	v_exp_f32_e32 v37, v37
	v_mul_f32_e32 v32, v60, v32
	v_add_f32_e32 v37, 1.0, v37
	v_rcp_f32_e32 v37, v37
	s_nop 0
	v_mul_f32_e32 v36, v36, v37
	v_mul_f32_e32 v32, v32, v36
	v_cvt_pk_bf16_f32 v32, v32, s0
	ds_write_b16 v76, v32 offset:3456
	v_mul_f32_e32 v32, 0x4b800000, v33
	v_cndmask_b32_e32 v32, v33, v32, vcc
	v_rsq_f32_e32 v32, v32
	s_nop 0
	v_mul_f32_e32 v33, 0x45800000, v32
	v_cndmask_b32_e32 v32, v32, v33, vcc
	v_mul_f32_e32 v33, v45, v32
	v_mul_f32_e32 v36, 0xbfb8aa3b, v33
	v_exp_f32_e32 v36, v36
	v_mul_f32_e32 v32, v61, v32
	v_add_f32_e32 v36, 1.0, v36
	v_rcp_f32_e32 v36, v36
	s_nop 0
	v_mul_f32_e32 v33, v33, v36
	v_mul_f32_e32 v32, v32, v33
	v_cvt_pk_bf16_f32 v32, v32, s0
	ds_write_b16 v76, v32 offset:3600
	v_pk_fma_f32 v[32:33], v[34:35], s[6:7], v[74:75] op_sel_hi:[1,0,0]
	s_nop 0
	v_mul_f32_e32 v34, 0x4b800000, v32
	v_cmp_gt_f32_e64 s[0:1], s60, v32
	v_cmp_gt_f32_e32 vcc, s60, v33
	s_nop 0
	v_cndmask_b32_e64 v32, v32, v34, s[0:1]
	v_rsq_f32_e32 v32, v32
	s_nop 0
	v_mul_f32_e32 v34, 0x45800000, v32
	v_cndmask_b32_e64 v32, v32, v34, s[0:1]
	v_mul_f32_e32 v34, v46, v32
	v_mul_f32_e32 v35, 0xbfb8aa3b, v34
	v_exp_f32_e32 v35, v35
	v_mul_f32_e32 v32, v62, v32
	v_add_f32_e32 v35, 1.0, v35
	v_rcp_f32_e32 v35, v35
	s_nop 0
	v_mul_f32_e32 v34, v34, v35
	v_mul_f32_e32 v32, v32, v34
	v_cvt_pk_bf16_f32 v32, v32, s0
	ds_write_b16 v76, v32 offset:3744
	v_mul_f32_e32 v32, 0x4b800000, v33
	v_cndmask_b32_e32 v32, v33, v32, vcc
	v_rsq_f32_e32 v32, v32
	s_nop 0
	v_mul_f32_e32 v33, 0x45800000, v32
	v_cndmask_b32_e32 v32, v32, v33, vcc
	v_mul_f32_e32 v33, v47, v32
	v_mul_f32_e32 v34, 0xbfb8aa3b, v33
	v_exp_f32_e32 v34, v34
	v_mul_f32_e32 v32, v63, v32
	v_add_f32_e32 v34, 1.0, v34
	v_rcp_f32_e32 v34, v34
	s_nop 0
	v_mul_f32_e32 v33, v33, v34
	v_mul_f32_e32 v32, v32, v33
	v_cvt_pk_bf16_f32 v32, v32, s0
	ds_write_b16 v76, v32 offset:3888
	v_or_b32_e32 v32, 32, v78
	v_ashrrev_i32_e32 v33, 31, v32
	v_lshl_add_u64 v[32:33], v[32:33], 2, s[4:5]
	v_subrev_u32_e32 v167, s30, v32
	ds_read_b128 v[32:35], v167 offset:50176
	s_waitcnt lgkmcnt(0)
	v_pk_fma_f32 v[32:33], v[32:33], s[6:7], v[74:75] op_sel_hi:[1,0,0]
	s_nop 0
	v_mul_f32_e32 v36, 0x4b800000, v32
	v_cmp_gt_f32_e64 s[0:1], s60, v32
	v_cmp_gt_f32_e32 vcc, s60, v33
	s_nop 0
	v_cndmask_b32_e64 v32, v32, v36, s[0:1]
	v_rsq_f32_e32 v32, v32
	s_nop 0
	v_mul_f32_e32 v36, 0x45800000, v32
	v_cndmask_b32_e64 v32, v32, v36, s[0:1]
	v_mul_f32_e32 v0, v0, v32
	v_mul_f32_e32 v16, v16, v32
	v_mul_f32_e32 v32, 0xbfb8aa3b, v0
	v_exp_f32_e32 v32, v32
	s_nop 0
	v_add_f32_e32 v32, 1.0, v32
	v_rcp_f32_e32 v32, v32
	s_nop 0
	v_mul_f32_e32 v0, v0, v32
	v_mul_f32_e32 v0, v16, v0
	v_cvt_pk_bf16_f32 v0, v0, s0
	ds_write_b16 v76, v0 offset:4608
	v_mul_f32_e32 v0, 0x4b800000, v33
	v_cndmask_b32_e32 v0, v33, v0, vcc
	v_rsq_f32_e32 v0, v0
	s_nop 0
	v_mul_f32_e32 v16, 0x45800000, v0
	v_cndmask_b32_e32 v0, v0, v16, vcc
	v_mul_f32_e32 v1, v1, v0
	v_mul_f32_e32 v16, 0xbfb8aa3b, v1
	v_exp_f32_e32 v16, v16
	v_mul_f32_e32 v0, v17, v0
	v_add_f32_e32 v16, 1.0, v16
	v_rcp_f32_e32 v16, v16
	s_nop 0
	v_mul_f32_e32 v1, v1, v16
	v_mul_f32_e32 v0, v0, v1
	v_cvt_pk_bf16_f32 v0, v0, s0
	ds_write_b16 v76, v0 offset:4752
	v_pk_fma_f32 v[0:1], v[34:35], s[6:7], v[74:75] op_sel_hi:[1,0,0]
	s_nop 0
	v_mul_f32_e32 v16, 0x4b800000, v0
	v_cmp_gt_f32_e64 s[0:1], s60, v0
	v_cmp_gt_f32_e32 vcc, s60, v1
	s_nop 0
	v_cndmask_b32_e64 v0, v0, v16, s[0:1]
	v_rsq_f32_e32 v0, v0
	s_nop 0
	v_mul_f32_e32 v16, 0x45800000, v0
	v_cndmask_b32_e64 v0, v0, v16, s[0:1]
	v_mul_f32_e32 v2, v2, v0
	v_mul_f32_e32 v16, 0xbfb8aa3b, v2
	v_exp_f32_e32 v16, v16
	v_mul_f32_e32 v0, v18, v0
	v_add_f32_e32 v16, 1.0, v16
	v_rcp_f32_e32 v16, v16
	s_nop 0
	v_mul_f32_e32 v2, v2, v16
	v_mul_f32_e32 v0, v0, v2
	v_cvt_pk_bf16_f32 v0, v0, s0
	ds_write_b16 v76, v0 offset:4896
	v_mul_f32_e32 v0, 0x4b800000, v1
	v_cndmask_b32_e32 v0, v1, v0, vcc
	v_rsq_f32_e32 v0, v0
	s_nop 0
	v_mul_f32_e32 v1, 0x45800000, v0
	v_cndmask_b32_e32 v0, v0, v1, vcc
	v_mul_f32_e32 v1, v3, v0
	v_mul_f32_e32 v2, 0xbfb8aa3b, v1
	v_exp_f32_e32 v2, v2
	v_mul_f32_e32 v0, v19, v0
	v_add_f32_e32 v2, 1.0, v2
	v_rcp_f32_e32 v2, v2
	s_nop 0
	v_mul_f32_e32 v1, v1, v2
	v_mul_f32_e32 v0, v0, v1
	v_cvt_pk_bf16_f32 v0, v0, s0
	ds_write_b16 v76, v0 offset:5040
	v_or_b32_e32 v0, 40, v78
	v_ashrrev_i32_e32 v1, 31, v0
	v_lshl_add_u64 v[0:1], v[0:1], 2, s[4:5]
	v_subrev_u32_e32 v167, s30, v0
	ds_read_b128 v[0:3], v167 offset:50176
	s_waitcnt lgkmcnt(0)
	v_pk_fma_f32 v[0:1], v[0:1], s[6:7], v[74:75] op_sel_hi:[1,0,0]
	s_nop 0
	v_mul_f32_e32 v16, 0x4b800000, v0
	v_cmp_gt_f32_e64 s[0:1], s60, v0
	v_cmp_gt_f32_e32 vcc, s60, v1
	s_nop 0
	v_cndmask_b32_e64 v0, v0, v16, s[0:1]
	v_rsq_f32_e32 v0, v0
	s_nop 0
	v_mul_f32_e32 v16, 0x45800000, v0
	v_cndmask_b32_e64 v0, v0, v16, s[0:1]
	v_mul_f32_e32 v4, v4, v0
	v_mul_f32_e32 v16, 0xbfb8aa3b, v4
	v_exp_f32_e32 v16, v16
	v_mul_f32_e32 v0, v20, v0
	v_add_f32_e32 v16, 1.0, v16
	v_rcp_f32_e32 v16, v16
	s_nop 0
	v_mul_f32_e32 v4, v4, v16
	v_mul_f32_e32 v0, v0, v4
	v_cvt_pk_bf16_f32 v0, v0, s0
	ds_write_b16 v76, v0 offset:5760
	v_mul_f32_e32 v0, 0x4b800000, v1
	v_cndmask_b32_e32 v0, v1, v0, vcc
	v_rsq_f32_e32 v0, v0
	s_nop 0
	v_mul_f32_e32 v1, 0x45800000, v0
	v_cndmask_b32_e32 v0, v0, v1, vcc
	v_mul_f32_e32 v1, v5, v0
	v_mul_f32_e32 v4, 0xbfb8aa3b, v1
	v_exp_f32_e32 v4, v4
	v_mul_f32_e32 v0, v21, v0
	v_add_f32_e32 v4, 1.0, v4
	v_rcp_f32_e32 v4, v4
	s_nop 0
	v_mul_f32_e32 v1, v1, v4
	v_mul_f32_e32 v0, v0, v1
	v_cvt_pk_bf16_f32 v0, v0, s0
	ds_write_b16 v76, v0 offset:5904
	v_pk_fma_f32 v[0:1], v[2:3], s[6:7], v[74:75] op_sel_hi:[1,0,0]
	s_nop 0
	v_mul_f32_e32 v2, 0x4b800000, v0
	v_cmp_gt_f32_e64 s[0:1], s60, v0
	v_cmp_gt_f32_e32 vcc, s60, v1
	s_nop 0
	v_cndmask_b32_e64 v0, v0, v2, s[0:1]
	v_rsq_f32_e32 v0, v0
	s_nop 0
	v_mul_f32_e32 v2, 0x45800000, v0
	v_cndmask_b32_e64 v0, v0, v2, s[0:1]
	v_mul_f32_e32 v2, v6, v0
	v_mul_f32_e32 v3, 0xbfb8aa3b, v2
	v_exp_f32_e32 v3, v3
	v_mul_f32_e32 v0, v22, v0
	v_add_f32_e32 v3, 1.0, v3
	v_rcp_f32_e32 v3, v3
	s_nop 0
	v_mul_f32_e32 v2, v2, v3
	v_mul_f32_e32 v0, v0, v2
	v_cvt_pk_bf16_f32 v0, v0, s0
	ds_write_b16 v76, v0 offset:6048
	v_mul_f32_e32 v0, 0x4b800000, v1
	v_cndmask_b32_e32 v0, v1, v0, vcc
	v_rsq_f32_e32 v0, v0
	s_nop 0
	v_mul_f32_e32 v1, 0x45800000, v0
	v_cndmask_b32_e32 v0, v0, v1, vcc
	v_mul_f32_e32 v1, v7, v0
	v_mul_f32_e32 v2, 0xbfb8aa3b, v1
	v_exp_f32_e32 v2, v2
	v_mul_f32_e32 v0, v23, v0
	v_add_f32_e32 v2, 1.0, v2
	v_rcp_f32_e32 v2, v2
	s_nop 0
	v_mul_f32_e32 v1, v1, v2
	v_mul_f32_e32 v0, v0, v1
	v_cvt_pk_bf16_f32 v0, v0, s0
	ds_write_b16 v76, v0 offset:6192
	v_or_b32_e32 v0, 48, v78
	v_ashrrev_i32_e32 v1, 31, v0
	v_lshl_add_u64 v[0:1], v[0:1], 2, s[4:5]
	v_subrev_u32_e32 v167, s30, v0
	ds_read_b128 v[0:3], v167 offset:50176
	s_waitcnt lgkmcnt(0)
	v_pk_fma_f32 v[0:1], v[0:1], s[6:7], v[74:75] op_sel_hi:[1,0,0]
	s_nop 0
	v_mul_f32_e32 v4, 0x4b800000, v0
	v_cmp_gt_f32_e64 s[0:1], s60, v0
	v_cmp_gt_f32_e32 vcc, s60, v1
	s_nop 0
	v_cndmask_b32_e64 v0, v0, v4, s[0:1]
	v_rsq_f32_e32 v0, v0
	s_nop 0
	v_mul_f32_e32 v4, 0x45800000, v0
	v_cndmask_b32_e64 v0, v0, v4, s[0:1]
	v_mul_f32_e32 v4, v8, v0
	v_mul_f32_e32 v5, 0xbfb8aa3b, v4
	v_exp_f32_e32 v5, v5
	v_mul_f32_e32 v0, v24, v0
	v_add_f32_e32 v5, 1.0, v5
	v_rcp_f32_e32 v5, v5
	s_nop 0
	v_mul_f32_e32 v4, v4, v5
	v_mul_f32_e32 v0, v0, v4
	v_cvt_pk_bf16_f32 v0, v0, s0
	ds_write_b16 v76, v0 offset:6912
	v_mul_f32_e32 v0, 0x4b800000, v1
	v_cndmask_b32_e32 v0, v1, v0, vcc
	v_rsq_f32_e32 v0, v0
	s_nop 0
	v_mul_f32_e32 v1, 0x45800000, v0
	v_cndmask_b32_e32 v0, v0, v1, vcc
	v_mul_f32_e32 v1, v9, v0
	v_mul_f32_e32 v4, 0xbfb8aa3b, v1
	v_exp_f32_e32 v4, v4
	v_mul_f32_e32 v0, v25, v0
	v_add_f32_e32 v4, 1.0, v4
	v_rcp_f32_e32 v4, v4
	s_nop 0
	v_mul_f32_e32 v1, v1, v4
	v_mul_f32_e32 v0, v0, v1
	v_cvt_pk_bf16_f32 v0, v0, s0
	ds_write_b16 v76, v0 offset:7056
	v_pk_fma_f32 v[0:1], v[2:3], s[6:7], v[74:75] op_sel_hi:[1,0,0]
	s_nop 0
	v_mul_f32_e32 v2, 0x4b800000, v0
	v_cmp_gt_f32_e64 s[0:1], s60, v0
	v_cmp_gt_f32_e32 vcc, s60, v1
	s_nop 0
	v_cndmask_b32_e64 v0, v0, v2, s[0:1]
	v_rsq_f32_e32 v0, v0
	s_nop 0
	v_mul_f32_e32 v2, 0x45800000, v0
	v_cndmask_b32_e64 v0, v0, v2, s[0:1]
	v_mul_f32_e32 v2, v10, v0
	v_mul_f32_e32 v3, 0xbfb8aa3b, v2
	v_exp_f32_e32 v3, v3
	v_mul_f32_e32 v0, v26, v0
	v_add_f32_e32 v3, 1.0, v3
	v_rcp_f32_e32 v3, v3
	s_nop 0
	v_mul_f32_e32 v2, v2, v3
	v_mul_f32_e32 v0, v0, v2
	v_cvt_pk_bf16_f32 v0, v0, s0
	ds_write_b16 v76, v0 offset:7200
	v_mul_f32_e32 v0, 0x4b800000, v1
	v_cndmask_b32_e32 v0, v1, v0, vcc
	v_rsq_f32_e32 v0, v0
	s_nop 0
	v_mul_f32_e32 v1, 0x45800000, v0
	v_cndmask_b32_e32 v0, v0, v1, vcc
	v_mul_f32_e32 v1, v11, v0
	v_mul_f32_e32 v2, 0xbfb8aa3b, v1
	v_exp_f32_e32 v2, v2
	v_mul_f32_e32 v0, v27, v0
	v_mov_b32_e32 v11, v65
	v_add_f32_e32 v2, 1.0, v2
	v_rcp_f32_e32 v2, v2
	s_nop 0
	v_mul_f32_e32 v1, v1, v2
	v_mul_f32_e32 v0, v0, v1
	v_cvt_pk_bf16_f32 v0, v0, s0
	ds_write_b16 v76, v0 offset:7344
	v_or_b32_e32 v0, 56, v78
	v_ashrrev_i32_e32 v1, 31, v0
	v_lshl_add_u64 v[0:1], v[0:1], 2, s[4:5]
	v_subrev_u32_e32 v167, s30, v0
	ds_read_b128 v[0:3], v167 offset:50176
	s_waitcnt lgkmcnt(0)
	v_pk_fma_f32 v[0:1], v[0:1], s[6:7], v[74:75] op_sel_hi:[1,0,0]
	s_nop 0
	v_mul_f32_e32 v4, 0x4b800000, v0
	v_cmp_gt_f32_e64 s[0:1], s60, v0
	v_cmp_gt_f32_e32 vcc, s60, v1
	s_nop 0
	v_cndmask_b32_e64 v0, v0, v4, s[0:1]
	v_rsq_f32_e32 v0, v0
	s_nop 0
	v_mul_f32_e32 v4, 0x45800000, v0
	v_cndmask_b32_e64 v0, v0, v4, s[0:1]
	v_mul_f32_e32 v4, v12, v0
	v_mul_f32_e32 v5, 0xbfb8aa3b, v4
	v_exp_f32_e32 v5, v5
	v_mul_f32_e32 v0, v28, v0
	v_add_f32_e32 v5, 1.0, v5
	v_rcp_f32_e32 v5, v5
	s_nop 0
	v_mul_f32_e32 v4, v4, v5
	v_mul_f32_e32 v0, v0, v4
	v_cvt_pk_bf16_f32 v0, v0, s0
	ds_write_b16 v76, v0 offset:8064
	v_mul_f32_e32 v0, 0x4b800000, v1
	v_cndmask_b32_e32 v0, v1, v0, vcc
	v_rsq_f32_e32 v0, v0
	v_ashrrev_i32_e32 v5, 3, v73
	v_add_u32_e32 v8, s11, v5
	v_ashrrev_i32_e32 v8, 7, v8
	v_mul_f32_e32 v1, 0x45800000, v0
	v_cndmask_b32_e32 v0, v0, v1, vcc
	v_mul_f32_e32 v1, v13, v0
	v_mul_f32_e32 v4, 0xbfb8aa3b, v1
	v_exp_f32_e32 v4, v4
	v_mul_f32_e32 v0, v29, v0
	v_mul_lo_u32 v8, v8, s61
	v_ashrrev_i32_e32 v9, 31, v8
	v_add_f32_e32 v4, 1.0, v4
	v_rcp_f32_e32 v4, v4
	s_nop 0
	v_mul_f32_e32 v1, v1, v4
	v_mul_f32_e32 v0, v0, v1
	v_cvt_pk_bf16_f32 v0, v0, s0
	ds_write_b16 v76, v0 offset:8208
	v_pk_fma_f32 v[0:1], v[2:3], s[6:7], v[74:75] op_sel_hi:[1,0,0]
	s_nop 0
	v_mul_f32_e32 v2, 0x4b800000, v0
	v_cmp_gt_f32_e64 s[0:1], s60, v0
	v_cmp_gt_f32_e32 vcc, s60, v1
	s_nop 0
	v_cndmask_b32_e64 v0, v0, v2, s[0:1]
	v_rsq_f32_e32 v0, v0
	s_nop 0
	v_mul_f32_e32 v2, 0x45800000, v0
	v_cndmask_b32_e64 v0, v0, v2, s[0:1]
	v_mul_f32_e32 v2, v14, v0
	v_mul_f32_e32 v3, 0xbfb8aa3b, v2
	v_exp_f32_e32 v3, v3
	v_mul_f32_e32 v0, v30, v0
	v_add_f32_e32 v3, 1.0, v3
	v_rcp_f32_e32 v3, v3
	s_nop 0
	v_mul_f32_e32 v2, v2, v3
	v_mul_f32_e32 v0, v0, v2
	v_cvt_pk_bf16_f32 v0, v0, s0
	ds_write_b16 v76, v0 offset:8352
	v_mul_f32_e32 v0, 0x4b800000, v1
	v_cndmask_b32_e32 v0, v1, v0, vcc
	v_rsq_f32_e32 v0, v0
	s_nop 0
	v_mul_f32_e32 v1, 0x45800000, v0
	v_cndmask_b32_e32 v0, v0, v1, vcc
	v_mul_f32_e32 v1, v15, v0
	v_mul_f32_e32 v2, 0xbfb8aa3b, v1
	v_exp_f32_e32 v2, v2
	v_mul_f32_e32 v0, v31, v0
	v_add_f32_e32 v2, 1.0, v2
	v_rcp_f32_e32 v2, v2
	s_nop 0
	v_mul_f32_e32 v1, v1, v2
	v_mul_f32_e32 v0, v0, v1
	v_cvt_pk_bf16_f32 v0, v0, s0
	ds_write_b16 v76, v0 offset:8496
	v_lshlrev_b32_e32 v0, 3, v73
	v_and_b32_e32 v0, 56, v0
	v_lshlrev_b32_e32 v4, 1, v0
	v_lshl_or_b32 v0, s10, 6, v0
	v_ashrrev_i32_e32 v6, 5, v0
	v_ashrrev_i32_e32 v7, 31, v6
	v_mad_u64_u32 v[0:1], s[0:1], v5, s59, v[4:5]
	s_waitcnt lgkmcnt(0)
	s_barrier
	ds_read_b128 v[0:3], v0
	v_lshl_add_u64 v[8:9], v[8:9], 0, v[6:7]
	v_lshlrev_b64 v[8:9], 13, v[8:9]
	v_lshlrev_b32_e32 v5, 6, v5
	v_lshl_add_u64 v[8:9], s[46:47], 0, v[8:9]
	v_and_b32_e32 v64, 0x1fc0, v5
	v_lshlrev_b32_e32 v5, 4, v73
	v_lshl_add_u64 v[8:9], v[8:9], 0, v[64:65]
	v_and_b32_e32 v64, 48, v5
	v_lshl_add_u64 v[8:9], v[8:9], 0, v[64:65]
	s_waitcnt lgkmcnt(0)
	global_store_dwordx4 v[8:9], v[0:3], off
	s_nop 1
	v_add_u32_e32 v0, 0x100, v73
	v_ashrrev_i32_e32 v5, 3, v0
	v_add_u32_e32 v8, s11, v5
	v_ashrrev_i32_e32 v8, 7, v8
	v_mul_lo_u32 v8, v8, s61
	v_mad_u64_u32 v[0:1], s[0:1], v5, s59, v[4:5]
	v_ashrrev_i32_e32 v9, 31, v8
	ds_read_b128 v[0:3], v0
	v_lshl_add_u64 v[8:9], v[8:9], 0, v[6:7]
	v_lshlrev_b64 v[8:9], 13, v[8:9]
	v_lshlrev_b32_e32 v5, 6, v5
	v_lshl_add_u64 v[8:9], s[46:47], 0, v[8:9]
	v_and_b32_e32 v10, 0x1fc0, v5
	v_lshl_add_u64 v[8:9], v[8:9], 0, v[10:11]
	v_lshl_add_u64 v[8:9], v[8:9], 0, v[64:65]
	s_waitcnt lgkmcnt(0)
	global_store_dwordx4 v[8:9], v[0:3], off
	s_nop 1
	v_add_u32_e32 v0, 0x200, v73
	v_ashrrev_i32_e32 v5, 3, v0
	v_add_u32_e32 v8, s11, v5
	v_ashrrev_i32_e32 v8, 7, v8
	v_mul_lo_u32 v8, v8, s61
	v_mad_u64_u32 v[0:1], s[0:1], v5, s59, v[4:5]
	v_ashrrev_i32_e32 v9, 31, v8
	ds_read_b128 v[0:3], v0
	v_lshl_add_u64 v[8:9], v[8:9], 0, v[6:7]
	v_lshlrev_b64 v[8:9], 13, v[8:9]
	v_lshlrev_b32_e32 v5, 6, v5
	v_lshl_add_u64 v[8:9], s[46:47], 0, v[8:9]
	v_and_b32_e32 v10, 0x1fc0, v5
	v_lshl_add_u64 v[8:9], v[8:9], 0, v[10:11]
	v_lshl_add_u64 v[8:9], v[8:9], 0, v[64:65]
	s_waitcnt lgkmcnt(0)
	global_store_dwordx4 v[8:9], v[0:3], off
	s_nop 1
	v_add_u32_e32 v0, 0x300, v73
	v_ashrrev_i32_e32 v8, 3, v0
	v_mad_u64_u32 v[0:1], s[0:1], v8, s59, v[4:5]
	v_add_u32_e32 v4, s11, v8
	v_ashrrev_i32_e32 v4, 7, v4
	v_mul_lo_u32 v4, v4, s61
	v_ashrrev_i32_e32 v5, 31, v4
	ds_read_b128 v[0:3], v0
	v_lshl_add_u64 v[4:5], v[4:5], 0, v[6:7]
	v_lshlrev_b64 v[4:5], 13, v[4:5]
	v_lshlrev_b32_e32 v6, 6, v8
	v_lshl_add_u64 v[4:5], s[46:47], 0, v[4:5]
	v_and_b32_e32 v6, 0x1fc0, v6
	v_mov_b32_e32 v7, v65
	v_lshl_add_u64 v[4:5], v[4:5], 0, v[6:7]
	v_lshl_add_u64 v[4:5], v[4:5], 0, v[64:65]
	s_waitcnt lgkmcnt(0)
	global_store_dwordx4 v[4:5], v[0:3], off

.Lg4a_hdr:
	s_cmp_ge_u32 s8, 128
	s_cbranch_scc1 .Lg4a_lastgrp
	s_mul_hi_u32 s0, s8, 0x4000000
	s_mul_i32 s1, s0, 64
	s_sub_i32 s1, s8, s1
	s_lshr_b32 s4, s1, 4
	s_and_b32 s3, s1, 15
	s_lshl_b32 s0, s0, 4
	s_add_u32 s3, s0, s3
	s_branch .Lg4a_cont

.Lg1b_epi:
	v_mov_b32_e32 v65, 0
	v_mov_b32_e32 v73, v148
	s_barrier
	s_movk_i32 s1, 0xffc0
	v_lshrrev_b32_e32 v74, 3, v73
	v_ashrrev_i32_e32 v64, 1, v73
	v_and_b32_e32 v74, 4, v74
	v_and_or_b32 v64, v64, s1, v74
	s_lshl_b32 s62, s4, 7
	v_add_u32_e32 v74, s62, v64
	v_ashrrev_i32_e32 v75, 31, v74
	v_lshl_add_u64 v[74:75], v[74:75], 2, s[90:91]
	v_subrev_u32_e32 v166, s30, v74
	ds_read_b128 v[80:83], v166 offset:50176
	v_and_b32_e32 v76, 0x5f, v73
	v_mul_lo_u32 v64, v64, s59
	v_lshl_add_u32 v64, v76, 1, v64
	s_lshl_b32 s4, s0, 7
	s_and_b32 s1, s0, -4
	s_mov_b64 s[6:7], -1
	s_cmp_lg_u32 s1, 4
	s_waitcnt lgkmcnt(0)
	v_mul_f32_e32 v32, v32, v80
	v_cvt_pk_bf16_f32 v32, v32, s0
	ds_write_b16 v64, v32 offset:64
	v_mul_f32_e32 v32, v49, v81
	v_cvt_pk_bf16_f32 v32, v32, s0
	ds_write_b16 v64, v32 offset:272
	v_mul_f32_e32 v32, v33, v81
	v_cvt_pk_bf16_f32 v32, v32, s0
	ds_write_b16 v64, v32 offset:336
	v_mul_f32_e32 v32, v50, v82
	v_cvt_pk_bf16_f32 v32, v32, s0
	ds_write_b16 v64, v32 offset:544
	v_mul_f32_e32 v32, v34, v82
	v_cvt_pk_bf16_f32 v32, v32, s0
	ds_write_b16 v64, v32 offset:608
	v_mul_f32_e32 v32, v51, v83
	v_cvt_pk_bf16_f32 v32, v32, s0
	ds_write_b16 v64, v32 offset:816
	v_mul_f32_e32 v32, v35, v83
	v_cvt_pk_bf16_f32 v32, v32, s0
	ds_write_b16 v64, v32 offset:880
	v_subrev_u32_e32 v166, s30, v74
	ds_read_b128 v[32:35], v166 offset:50208
	v_mul_f32_e32 v48, v48, v80
	v_cvt_pk_bf16_f32 v48, v48, s0
	ds_write_b16 v64, v48
	s_waitcnt lgkmcnt(0)
	v_mul_f32_e32 v48, v52, v32
	v_mul_f32_e32 v32, v36, v32
	v_cvt_pk_bf16_f32 v32, v32, s0
	ds_write_b16 v64, v32 offset:2240
	v_mul_f32_e32 v32, v53, v33
	v_cvt_pk_bf16_f32 v32, v32, s0
	ds_write_b16 v64, v32 offset:2448
	v_mul_f32_e32 v32, v37, v33
	v_cvt_pk_bf16_f32 v32, v32, s0
	ds_write_b16 v64, v32 offset:2512
	v_mul_f32_e32 v32, v54, v34
	v_cvt_pk_bf16_f32 v32, v32, s0
	ds_write_b16 v64, v32 offset:2720
	v_mul_f32_e32 v32, v38, v34
	v_cvt_pk_bf16_f32 v32, v32, s0
	ds_write_b16 v64, v32 offset:2784
	v_mul_f32_e32 v32, v55, v35
	v_cvt_pk_bf16_f32 v32, v32, s0
	ds_write_b16 v64, v32 offset:2992
	v_mul_f32_e32 v32, v39, v35
	v_cvt_pk_bf16_f32 v32, v32, s0
	ds_write_b16 v64, v32 offset:3056
	v_subrev_u32_e32 v166, s30, v74
	ds_read_b128 v[32:35], v166 offset:50240
	v_cvt_pk_bf16_f32 v48, v48, s0
	ds_write_b16 v64, v48 offset:2176
	s_waitcnt lgkmcnt(0)
	v_mul_f32_e32 v36, v56, v32
	v_mul_f32_e32 v32, v40, v32
	v_cvt_pk_bf16_f32 v32, v32, s0
	ds_write_b16 v64, v32 offset:4416
	v_mul_f32_e32 v32, v57, v33
	v_cvt_pk_bf16_f32 v32, v32, s0
	ds_write_b16 v64, v32 offset:4624
	v_mul_f32_e32 v32, v41, v33
	v_cvt_pk_bf16_f32 v32, v32, s0
	ds_write_b16 v64, v32 offset:4688
	v_mul_f32_e32 v32, v58, v34
	v_cvt_pk_bf16_f32 v32, v32, s0
	ds_write_b16 v64, v32 offset:4896
	v_mul_f32_e32 v32, v42, v34
	v_cvt_pk_bf16_f32 v32, v32, s0
	ds_write_b16 v64, v32 offset:4960
	v_mul_f32_e32 v32, v59, v35
	v_cvt_pk_bf16_f32 v32, v32, s0
	ds_write_b16 v64, v32 offset:5168
	v_mul_f32_e32 v32, v43, v35
	v_cvt_pk_bf16_f32 v32, v32, s0
	ds_write_b16 v64, v32 offset:5232
	v_subrev_u32_e32 v166, s30, v74
	ds_read_b128 v[32:35], v166 offset:50272
	v_cvt_pk_bf16_f32 v36, v36, s0
	ds_write_b16 v64, v36 offset:4352
	s_waitcnt lgkmcnt(0)
	v_mul_f32_e32 v36, v60, v32
	v_mul_f32_e32 v32, v44, v32
	v_cvt_pk_bf16_f32 v32, v32, s0
	ds_write_b16 v64, v32 offset:6592
	v_mul_f32_e32 v32, v61, v33
	v_cvt_pk_bf16_f32 v32, v32, s0
	ds_write_b16 v64, v32 offset:6800
	v_mul_f32_e32 v32, v45, v33
	v_cvt_pk_bf16_f32 v32, v32, s0
	ds_write_b16 v64, v32 offset:6864
	v_mul_f32_e32 v32, v62, v34
	v_cvt_pk_bf16_f32 v32, v32, s0
	ds_write_b16 v64, v32 offset:7072
	v_mul_f32_e32 v32, v46, v34
	v_cvt_pk_bf16_f32 v32, v32, s0
	ds_write_b16 v64, v32 offset:7136
	v_mul_f32_e32 v32, v63, v35
	v_cvt_pk_bf16_f32 v32, v32, s0
	ds_write_b16 v64, v32 offset:7344
	v_mul_f32_e32 v32, v47, v35
	v_cvt_pk_bf16_f32 v32, v32, s0
	ds_write_b16 v64, v32 offset:7408
	v_subrev_u32_e32 v166, s30, v74
	ds_read_b128 v[32:35], v166 offset:50304
	v_cvt_pk_bf16_f32 v36, v36, s0
	ds_write_b16 v64, v36 offset:6528
	s_waitcnt lgkmcnt(0)
	v_mul_f32_e32 v0, v0, v32
	v_cvt_pk_bf16_f32 v0, v0, s0
	ds_write_b16 v64, v0 offset:8768
	v_mul_f32_e32 v0, v17, v33
	v_cvt_pk_bf16_f32 v0, v0, s0
	ds_write_b16 v64, v0 offset:8976
	v_mul_f32_e32 v0, v1, v33
	v_cvt_pk_bf16_f32 v0, v0, s0
	ds_write_b16 v64, v0 offset:9040
	v_mul_f32_e32 v0, v18, v34
	v_cvt_pk_bf16_f32 v0, v0, s0
	ds_write_b16 v64, v0 offset:9248
	v_mul_f32_e32 v0, v2, v34
	v_cvt_pk_bf16_f32 v0, v0, s0
	ds_write_b16 v64, v0 offset:9312
	v_mul_f32_e32 v0, v19, v35
	v_cvt_pk_bf16_f32 v0, v0, s0
	ds_write_b16 v64, v0 offset:9520
	v_mul_f32_e32 v0, v3, v35
	v_cvt_pk_bf16_f32 v0, v0, s0
	ds_write_b16 v64, v0 offset:9584
	v_subrev_u32_e32 v166, s30, v74
	ds_read_b128 v[0:3], v166 offset:50336
	v_mul_f32_e32 v16, v16, v32
	v_cvt_pk_bf16_f32 v16, v16, s0
	ds_write_b16 v64, v16 offset:8704
	s_waitcnt lgkmcnt(0)
	v_mul_f32_e32 v16, v20, v0
	v_mul_f32_e32 v0, v4, v0
	v_cvt_pk_bf16_f32 v0, v0, s0
	ds_write_b16 v64, v0 offset:10944
	v_mul_f32_e32 v0, v21, v1
	v_cvt_pk_bf16_f32 v0, v0, s0
	ds_write_b16 v64, v0 offset:11152
	v_mul_f32_e32 v0, v5, v1
	v_cvt_pk_bf16_f32 v0, v0, s0
	ds_write_b16 v64, v0 offset:11216
	v_mul_f32_e32 v0, v22, v2
	v_cvt_pk_bf16_f32 v0, v0, s0
	ds_write_b16 v64, v0 offset:11424
	v_mul_f32_e32 v0, v6, v2
	v_cvt_pk_bf16_f32 v0, v0, s0
	ds_write_b16 v64, v0 offset:11488
	v_mul_f32_e32 v0, v23, v3
	v_cvt_pk_bf16_f32 v0, v0, s0
	ds_write_b16 v64, v0 offset:11696
	v_mul_f32_e32 v0, v7, v3
	v_cvt_pk_bf16_f32 v0, v0, s0
	ds_write_b16 v64, v0 offset:11760
	v_subrev_u32_e32 v166, s30, v74
	ds_read_b128 v[0:3], v166 offset:50368
	v_cvt_pk_bf16_f32 v16, v16, s0
	ds_write_b16 v64, v16 offset:10880
	s_waitcnt lgkmcnt(0)
	v_mul_f32_e32 v4, v24, v0
	v_mul_f32_e32 v0, v8, v0
	v_cvt_pk_bf16_f32 v0, v0, s0
	ds_write_b16 v64, v0 offset:13120
	v_mul_f32_e32 v0, v25, v1
	v_cvt_pk_bf16_f32 v0, v0, s0
	ds_write_b16 v64, v0 offset:13328
	v_mul_f32_e32 v0, v9, v1
	v_cvt_pk_bf16_f32 v0, v0, s0
	ds_write_b16 v64, v0 offset:13392
	v_mul_f32_e32 v0, v26, v2
	v_cvt_pk_bf16_f32 v0, v0, s0
	ds_write_b16 v64, v0 offset:13600
	v_mul_f32_e32 v0, v10, v2
	v_cvt_pk_bf16_f32 v0, v0, s0
	ds_write_b16 v64, v0 offset:13664
	v_mul_f32_e32 v0, v27, v3
	v_cvt_pk_bf16_f32 v0, v0, s0
	ds_write_b16 v64, v0 offset:13872
	v_mul_f32_e32 v0, v11, v3
	v_cvt_pk_bf16_f32 v0, v0, s0
	ds_write_b16 v64, v0 offset:13936
	v_subrev_u32_e32 v166, s30, v74
	ds_read_b128 v[0:3], v166 offset:50400
	v_cvt_pk_bf16_f32 v4, v4, s0
	ds_write_b16 v64, v4 offset:13056
	s_waitcnt lgkmcnt(0)
	v_mul_f32_e32 v4, v28, v0
	v_mul_f32_e32 v0, v12, v0
	v_cvt_pk_bf16_f32 v0, v0, s0
	ds_write_b16 v64, v0 offset:15296
	v_mul_f32_e32 v0, v29, v1
	v_cvt_pk_bf16_f32 v0, v0, s0
	ds_write_b16 v64, v0 offset:15504
	v_mul_f32_e32 v0, v13, v1
	v_cvt_pk_bf16_f32 v0, v0, s0
	ds_write_b16 v64, v0 offset:15568
	v_mul_f32_e32 v0, v30, v2
	v_cvt_pk_bf16_f32 v0, v0, s0
	ds_write_b16 v64, v0 offset:15776
	v_mul_f32_e32 v0, v14, v2
	v_cvt_pk_bf16_f32 v0, v0, s0
	ds_write_b16 v64, v0 offset:15840
	v_mul_f32_e32 v0, v31, v3
	v_cvt_pk_bf16_f32 v0, v0, s0
	ds_write_b16 v64, v0 offset:16048
	v_mul_f32_e32 v0, v15, v3
	v_cvt_pk_bf16_f32 v4, v4, s0
	v_cvt_pk_bf16_f32 v0, v0, s0
	ds_write_b16 v64, v4 offset:15232
	ds_write_b16 v64, v0 offset:16112
	s_waitcnt lgkmcnt(0)
	s_barrier
	s_cbranch_scc0 .LBB0_824
	s_sub_i32 s1, s0, 20
	s_add_i32 s2, s4, 0xfffff800
	s_cmp_lt_u32 s1, 10
	s_cselect_b32 s2, s2, -1
	s_mov_b64 s[6:7], 0

.Lg2b_hdr:
	s_cmp_ge_u32 s8, 128
	s_cbranch_scc1 .Lg2b_lastgrp
	s_mul_hi_u32 s2, s8, 0x4000000
	s_mul_i32 s3, s2, 64
	s_sub_i32 s3, s8, s3
	s_lshr_b32 s6, s3, 4
	s_and_b32 s5, s3, 15
	s_lshl_b32 s2, s2, 4
	s_add_u32 s5, s2, s5
	s_branch .Lg2b_cont

.Lg3b_hdr:
	s_cmp_ge_u32 s9, 704
	s_cbranch_scc1 .Lg3b_lastgrp
	s_mul_hi_u32 s1, s9, 0xba2e8c
	s_mul_i32 s4, s1, 352
	s_sub_i32 s4, s9, s4
	s_lshr_b32 s7, s4, 4
	s_and_b32 s6, s4, 15
	s_lshl_b32 s1, s1, 4
	s_add_u32 s6, s1, s6
	s_branch .Lg3b_cont

.Lg3b_cont:
	s_lshl3_add_u32 s26, s6, s29
	s_lshl_b32 s27, s7, 1
	s_mul_i32 s1, s26, 0x40000
	s_add_u32 s18, s44, s1
	s_addc_u32 s19, s45, 0
	s_mul_i32 s1, s27, 0x40000
	s_add_u32 s1, s1, 0xd80000
	s_add_u32 s20, s48, s1
	s_addc_u32 s21, s49, 0
	s_add_u32 s22, s20, 0x40000
	s_addc_u32 s23, s21, 0
	s_lshl_b32 s1, s26, 9
	s_add_u32 s34, s2, s1
	s_addc_u32 s35, s3, 0
	s_waitcnt vmcnt(0) lgkmcnt(0)
	s_barrier
	v_and_b32_e32 v167, 63, v148
	v_lshlrev_b32_e32 v167, 4, v167
	s_mov_b32 m0, 0xc400
	s_mov_b64 exec, 0xffffffff
	global_load_lds_dwordx4 v167, s[34:35]
	s_mov_b64 exec, -1
	s_add_u32 m0, s24, 0x0
	s_nop 0
	global_load_lds_dwordx4 v164, s[18:19]
	global_load_lds_dwordx4 v164, s[18:19] offset:1024
	s_add_u32 s18, s18, 0x2000
	s_addc_u32 s19, s19, 0
	s_add_u32 m0, s24, 0x2000
	s_nop 0
	global_load_lds_dwordx4 v164, s[20:21]
	global_load_lds_dwordx4 v164, s[20:21] offset:1024
	s_add_u32 s20, s20, 0x2000
	s_addc_u32 s21, s21, 0
	s_add_u32 m0, s24, 0x4000
	s_nop 0
	global_load_lds_dwordx4 v164, s[22:23]
	global_load_lds_dwordx4 v164, s[22:23] offset:1024
	s_add_u32 s22, s22, 0x2000
	s_addc_u32 s23, s23, 0
	s_waitcnt vmcnt(0)
	s_barrier
	s_add_u32 m0, s24, 0x6000
	s_nop 0
	global_load_lds_dwordx4 v164, s[18:19]
	global_load_lds_dwordx4 v164, s[18:19] offset:1024
	s_add_u32 s18, s18, 0x2000
	s_addc_u32 s19, s19, 0
	s_add_u32 m0, s24, 0x8000
	s_nop 0
	global_load_lds_dwordx4 v164, s[20:21]
	global_load_lds_dwordx4 v164, s[20:21] offset:1024
	s_add_u32 s20, s20, 0x2000
	s_addc_u32 s21, s21, 0
	s_add_u32 m0, s24, 0xa400
	s_nop 0
	global_load_lds_dwordx4 v164, s[22:23]
	global_load_lds_dwordx4 v164, s[22:23] offset:1024
	s_add_u32 s22, s22, 0x2000
	s_addc_u32 s23, s23, 0
	ds_read_b128 v[64:67], v160 offset:0
	ds_read_b128 v[90:93], v162 offset:8192
	ds_read_b128 v[142:145], v162 offset:10240
	ds_read_b128 v[150:153], v162 offset:16384
	ds_read_b128 v[154:157], v162 offset:18432
	ds_read_b128 v[68:71], v160 offset:2048
	s_waitcnt lgkmcnt(4)
	v_mfma_f32_32x32x16_bf16 v[48:63], v[64:67], v[90:93], 0
	s_waitcnt lgkmcnt(3)
	v_mfma_f32_32x32x16_bf16 v[32:47], v[64:67], v[142:145], 0
	s_waitcnt lgkmcnt(2)
	v_mfma_f32_32x32x16_bf16 v[94:109], v[64:67], v[150:153], 0
	s_waitcnt lgkmcnt(1)
	v_mfma_f32_32x32x16_bf16 v[110:125], v[64:67], v[154:157], 0
	ds_read_b128 v[64:67], v161 offset:0
	s_waitcnt lgkmcnt(1)
	v_mfma_f32_32x32x16_bf16 v[74:89], v[68:71], v[154:157], 0
	ds_read_b128 v[154:157], v163 offset:18432
	v_mfma_f32_32x32x16_bf16 v[126:141], v[68:71], v[150:153], 0
	ds_read_b128 v[150:153], v163 offset:16384
	v_mfma_f32_32x32x16_bf16 v[0:15], v[68:71], v[142:145], 0
	ds_read_b128 v[142:145], v163 offset:10240
	v_mfma_f32_32x32x16_bf16 v[16:31], v[68:71], v[90:93], 0
	ds_read_b128 v[90:93], v163 offset:8192
	ds_read_b128 v[68:71], v161 offset:2048
	s_waitcnt lgkmcnt(4)
	v_mfma_f32_32x32x16_bf16 v[110:125], v[64:67], v[154:157], v[110:125]
	s_waitcnt lgkmcnt(3)
	v_mfma_f32_32x32x16_bf16 v[94:109], v[64:67], v[150:153], v[94:109]
	s_waitcnt lgkmcnt(2)
	v_mfma_f32_32x32x16_bf16 v[32:47], v[64:67], v[142:145], v[32:47]
	s_waitcnt lgkmcnt(1)
	v_mfma_f32_32x32x16_bf16 v[48:63], v[64:67], v[90:93], v[48:63]
	s_waitcnt vmcnt(0) lgkmcnt(0)
	s_barrier
	ds_read_b128 v[64:67], v160 offset:24576
	s_add_u32 m0, s24, 0x0
	s_nop 0
	global_load_lds_dwordx4 v164, s[18:19]
	global_load_lds_dwordx4 v164, s[18:19] offset:1024
	s_add_u32 s18, s18, 0x2000
	s_addc_u32 s19, s19, 0
	v_mfma_f32_32x32x16_bf16 v[16:31], v[68:71], v[90:93], v[16:31]
	ds_read_b128 v[90:93], v162 offset:32768
	s_add_u32 m0, s24, 0x2000
	s_nop 0
	global_load_lds_dwordx4 v164, s[20:21]
	global_load_lds_dwordx4 v164, s[20:21] offset:1024
	s_add_u32 s20, s20, 0x2000
	s_addc_u32 s21, s21, 0
	v_mfma_f32_32x32x16_bf16 v[0:15], v[68:71], v[142:145], v[0:15]
	ds_read_b128 v[142:145], v162 offset:34816
	s_add_u32 m0, s24, 0x4000
	s_nop 0
	global_load_lds_dwordx4 v164, s[22:23]
	global_load_lds_dwordx4 v164, s[22:23] offset:1024
	s_add_u32 s22, s22, 0x2000
	s_addc_u32 s23, s23, 0
	v_mfma_f32_32x32x16_bf16 v[126:141], v[68:71], v[150:153], v[126:141]
	ds_read_b128 v[150:153], v162 offset:41984
	v_mfma_f32_32x32x16_bf16 v[74:89], v[68:71], v[154:157], v[74:89]
	ds_read_b128 v[154:157], v162 offset:44032
	ds_read_b128 v[68:71], v160 offset:26624
	s_waitcnt lgkmcnt(4)
	v_mfma_f32_32x32x16_bf16 v[48:63], v[64:67], v[90:93], v[48:63]
	s_waitcnt lgkmcnt(3)
	v_mfma_f32_32x32x16_bf16 v[32:47], v[64:67], v[142:145], v[32:47]
	s_waitcnt lgkmcnt(2)
	v_mfma_f32_32x32x16_bf16 v[94:109], v[64:67], v[150:153], v[94:109]
	s_waitcnt lgkmcnt(1)
	v_mfma_f32_32x32x16_bf16 v[110:125], v[64:67], v[154:157], v[110:125]
	ds_read_b128 v[64:67], v161 offset:24576
	s_waitcnt lgkmcnt(1)
	v_mfma_f32_32x32x16_bf16 v[74:89], v[68:71], v[154:157], v[74:89]
	ds_read_b128 v[154:157], v163 offset:44032
	v_mfma_f32_32x32x16_bf16 v[126:141], v[68:71], v[150:153], v[126:141]
	ds_read_b128 v[150:153], v163 offset:41984
	v_mfma_f32_32x32x16_bf16 v[0:15], v[68:71], v[142:145], v[0:15]
	ds_read_b128 v[142:145], v163 offset:34816
	v_mfma_f32_32x32x16_bf16 v[16:31], v[68:71], v[90:93], v[16:31]
	ds_read_b128 v[90:93], v163 offset:32768
	ds_read_b128 v[68:71], v161 offset:26624
	s_waitcnt lgkmcnt(4)
	v_mfma_f32_32x32x16_bf16 v[110:125], v[64:67], v[154:157], v[110:125]
	s_waitcnt lgkmcnt(3)
	v_mfma_f32_32x32x16_bf16 v[94:109], v[64:67], v[150:153], v[94:109]
	s_waitcnt lgkmcnt(2)
	v_mfma_f32_32x32x16_bf16 v[32:47], v[64:67], v[142:145], v[32:47]
	s_waitcnt lgkmcnt(1)
	v_mfma_f32_32x32x16_bf16 v[48:63], v[64:67], v[90:93], v[48:63]
	s_waitcnt vmcnt(0) lgkmcnt(0)
	s_barrier
	ds_read_b128 v[64:67], v160 offset:0
	s_add_u32 m0, s24, 0x6000
	s_nop 0
	global_load_lds_dwordx4 v164, s[18:19]
	global_load_lds_dwordx4 v164, s[18:19] offset:1024
	s_add_u32 s18, s18, 0x2000
	s_addc_u32 s19, s19, 0
	v_mfma_f32_32x32x16_bf16 v[16:31], v[68:71], v[90:93], v[16:31]
	ds_read_b128 v[90:93], v162 offset:8192
	s_add_u32 m0, s24, 0x8000
	s_nop 0
	global_load_lds_dwordx4 v164, s[20:21]
	global_load_lds_dwordx4 v164, s[20:21] offset:1024
	s_add_u32 s20, s20, 0x2000
	s_addc_u32 s21, s21, 0
	v_mfma_f32_32x32x16_bf16 v[0:15], v[68:71], v[142:145], v[0:15]
	ds_read_b128 v[142:145], v162 offset:10240
	s_add_u32 m0, s24, 0xa400
	s_nop 0
	global_load_lds_dwordx4 v164, s[22:23]
	global_load_lds_dwordx4 v164, s[22:23] offset:1024
	s_add_u32 s22, s22, 0x2000
	s_addc_u32 s23, s23, 0
	v_mfma_f32_32x32x16_bf16 v[126:141], v[68:71], v[150:153], v[126:141]
	ds_read_b128 v[150:153], v162 offset:16384
	v_mfma_f32_32x32x16_bf16 v[74:89], v[68:71], v[154:157], v[74:89]
	ds_read_b128 v[154:157], v162 offset:18432
	ds_read_b128 v[68:71], v160 offset:2048
	s_mov_b32 s25, 14

.Lg3b_epi:
	v_mov_b32_e32 v73, 0
	v_mov_b32_e32 v81, v148
	v_mov_b32_e32 v82, 0x358637bd
	v_mov_b32_e32 v83, 0
	s_barrier
	s_lshl_b32 s15, s0, 7
	v_lshrrev_b32_e32 v65, 3, v81
	v_ashrrev_i32_e32 v64, 1, v81
	v_and_b32_e32 v65, 4, v65
	v_and_or_b32 v66, v64, s60, v65
	v_add_u32_e32 v86, s15, v66
	v_ashrrev_i32_e32 v87, 31, v86
	v_lshl_add_u64 v[64:65], v[86:87], 2, s[2:3]
	v_subrev_u32_e32 v167, s34, v64
	ds_read_b128 v[90:93], v167 offset:50176
	v_or_b32_e32 v64, 8, v86
	v_ashrrev_i32_e32 v65, 31, v64
	v_lshl_add_u64 v[64:65], v[64:65], 2, s[2:3]
	v_subrev_u32_e32 v167, s34, v64
	ds_read_b128 v[68:71], v167 offset:50176
	v_and_b32_e32 v64, 31, v81
	v_lshlrev_b32_e32 v64, 1, v64
	v_and_or_b32 v64, v81, 64, v64
	v_mad_u64_u32 v[84:85], s[0:1], v66, s61, v[64:65]
	v_or_b32_e32 v64, 16, v86
	v_ashrrev_i32_e32 v65, 31, v64
	v_lshl_add_u64 v[64:65], v[64:65], 2, s[2:3]
	v_subrev_u32_e32 v167, s34, v64
	ds_read_b128 v[64:67], v167 offset:50176
	s_waitcnt lgkmcnt(0)
	v_pk_fma_f32 v[90:91], v[90:91], s[8:9], v[82:83] op_sel_hi:[1,0,0]
	v_pk_fma_f32 v[92:93], v[92:93], s[8:9], v[82:83] op_sel_hi:[1,0,0]
	v_mul_f32_e32 v72, 0x4b800000, v90
	v_mul_f32_e32 v85, 0x4b800000, v91
	v_mul_f32_e32 v87, 0x4b800000, v92
	v_mul_f32_e32 v89, 0x4b800000, v93
	s_waitcnt lgkmcnt(0)
	v_pk_fma_f32 v[68:69], v[68:69], s[8:9], v[82:83] op_sel_hi:[1,0,0]
	v_cmp_gt_f32_e32 vcc, s62, v90
	v_cmp_gt_f32_e64 s[0:1], s62, v91
	v_cmp_gt_f32_e64 s[4:5], s62, v92
	v_cmp_gt_f32_e64 s[6:7], s62, v93
	v_cndmask_b32_e32 v72, v90, v72, vcc
	v_cndmask_b32_e64 v85, v91, v85, s[0:1]
	v_cndmask_b32_e64 v87, v92, v87, s[4:5]
	v_cndmask_b32_e64 v89, v93, v89, s[6:7]
	v_mul_f32_e32 v90, 0x4b800000, v68
	v_cmp_gt_f32_e64 s[10:11], s62, v68
	v_rsq_f32_e32 v72, v72
	v_rsq_f32_e32 v85, v85
	v_rsq_f32_e32 v87, v87
	v_rsq_f32_e32 v89, v89
	v_cndmask_b32_e64 v68, v68, v90, s[10:11]
	v_rsq_f32_e32 v68, v68
	v_mul_f32_e32 v91, 0x4b800000, v69
	v_cmp_gt_f32_e64 s[12:13], s62, v69
	v_mul_f32_e32 v90, 0x45800000, v72
	v_mul_f32_e32 v92, 0x45800000, v87
	v_cndmask_b32_e64 v69, v69, v91, s[12:13]
	v_mul_f32_e32 v91, 0x45800000, v85
	v_mul_f32_e32 v93, 0x45800000, v89
	v_cndmask_b32_e32 v72, v72, v90, vcc
	v_cndmask_b32_e64 v85, v85, v91, s[0:1]
	v_cndmask_b32_e64 v87, v87, v92, s[4:5]
	v_cndmask_b32_e64 v89, v89, v93, s[6:7]
	v_mul_f32_e32 v90, 0x45800000, v68
	v_mul_f32_e32 v48, v48, v72
	v_mul_f32_e32 v49, v49, v85
	v_mul_f32_e32 v50, v50, v87
	v_mul_f32_e32 v51, v51, v89
	v_cndmask_b32_e64 v68, v68, v90, s[10:11]
	v_mul_f32_e32 v32, v32, v72
	v_mul_f32_e32 v33, v33, v85
	v_mul_f32_e32 v34, v34, v87
	v_mul_f32_e32 v35, v35, v89
	v_mul_f32_e32 v72, 0xbfb8aa3b, v48
	v_mul_f32_e32 v85, 0xbfb8aa3b, v49
	v_mul_f32_e32 v87, 0xbfb8aa3b, v50
	v_mul_f32_e32 v89, 0xbfb8aa3b, v51
	v_mul_f32_e32 v52, v52, v68
	v_mul_f32_e32 v36, v36, v68
	v_exp_f32_e32 v68, v72
	v_exp_f32_e32 v72, v85
	v_exp_f32_e32 v85, v87
	v_exp_f32_e32 v87, v89
	v_mul_f32_e32 v89, 0xbfb8aa3b, v52
	v_exp_f32_e32 v89, v89
	v_add_f32_e32 v68, 1.0, v68
	v_add_f32_e32 v72, 1.0, v72
	v_add_f32_e32 v85, 1.0, v85
	v_add_f32_e32 v87, 1.0, v87
	v_rcp_f32_e32 v68, v68
	v_add_f32_e32 v89, 1.0, v89
	v_rcp_f32_e32 v72, v72
	v_rcp_f32_e32 v85, v85
	v_rcp_f32_e32 v87, v87
	v_rcp_f32_e32 v89, v89
	v_rsq_f32_e32 v69, v69
	v_mul_f32_e32 v48, v48, v68
	v_mul_f32_e32 v49, v49, v72
	v_mul_f32_e32 v50, v50, v85
	v_mul_f32_e32 v51, v51, v87
	v_mul_f32_e32 v32, v32, v48
	v_mul_f32_e32 v48, v52, v89
	v_mul_f32_e32 v33, v33, v49
	v_mul_f32_e32 v34, v34, v50
	v_mul_f32_e32 v35, v35, v51
	v_cvt_pk_bf16_f32 v32, v32, s0
	v_mul_f32_e32 v36, v36, v48
	v_cvt_pk_bf16_f32 v33, v33, s0
	v_cvt_pk_bf16_f32 v34, v34, s0
	v_cvt_pk_bf16_f32 v35, v35, s0
	ds_write_b16 v84, v32
	ds_write_b16 v84, v33 offset:144
	ds_write_b16 v84, v34 offset:288
	ds_write_b16 v84, v35 offset:432
	v_cvt_pk_bf16_f32 v32, v36, s0
	ds_write_b16 v84, v32 offset:1152
	v_mul_f32_e32 v32, 0x45800000, v69
	v_cndmask_b32_e64 v34, v69, v32, s[12:13]
	v_mul_f32_e32 v35, v53, v34
	v_mul_f32_e32 v32, 0xbfb8aa3b, v35
	v_exp_f32_e32 v36, v32
	v_pk_fma_f32 v[32:33], v[70:71], s[8:9], v[82:83] op_sel_hi:[1,0,0]
	v_mul_f32_e32 v34, v37, v34
	v_mul_f32_e32 v48, 0x4b800000, v32
	v_cmp_gt_f32_e32 vcc, s62, v32
	v_add_f32_e32 v36, 1.0, v36
	v_rcp_f32_e32 v36, v36
	v_cndmask_b32_e32 v32, v32, v48, vcc
	v_rsq_f32_e32 v32, v32
	v_mul_f32_e32 v35, v35, v36
	v_mul_f32_e32 v36, 0x4b800000, v33
	v_mul_f32_e32 v37, 0x45800000, v32
	v_cndmask_b32_e32 v32, v32, v37, vcc
	v_cmp_gt_f32_e32 vcc, s62, v33
	v_mul_f32_e32 v37, v54, v32
	v_mul_f32_e32 v34, v34, v35
	v_cndmask_b32_e32 v33, v33, v36, vcc
	v_rsq_f32_e32 v33, v33
	v_mul_f32_e32 v48, 0xbfb8aa3b, v37
	v_cvt_pk_bf16_f32 v34, v34, s0
	v_exp_f32_e32 v48, v48
	ds_write_b16 v84, v34 offset:1296
	v_mul_f32_e32 v34, v38, v32
	v_mul_f32_e32 v32, 0x45800000, v33
	v_cndmask_b32_e32 v36, v33, v32, vcc
	v_or_b32_e32 v32, 24, v86
	v_ashrrev_i32_e32 v33, 31, v32
	v_lshl_add_u64 v[32:33], v[32:33], 2, s[2:3]
	v_add_f32_e32 v35, 1.0, v48
	v_subrev_u32_e32 v167, s34, v32
	ds_read_b128 v[48:51], v167 offset:50176
	v_rcp_f32_e32 v35, v35
	s_nop 0
	v_mul_f32_e32 v35, v37, v35
	v_mul_f32_e32 v37, v55, v36
	v_mul_f32_e32 v32, 0xbfb8aa3b, v37
	v_exp_f32_e32 v32, v32
	v_mul_f32_e32 v33, v34, v35
	v_cvt_pk_bf16_f32 v33, v33, s0
	ds_write_b16 v84, v33 offset:1440
	v_add_f32_e32 v32, 1.0, v32
	v_rcp_f32_e32 v34, v32
	s_waitcnt lgkmcnt(0)
	v_pk_fma_f32 v[32:33], v[64:65], s[8:9], v[82:83] op_sel_hi:[1,0,0]
	v_mul_f32_e32 v34, v37, v34
	v_mul_f32_e32 v35, 0x4b800000, v32
	v_cmp_gt_f32_e32 vcc, s62, v32
	s_nop 1
	v_cndmask_b32_e32 v32, v32, v35, vcc
	v_rsq_f32_e32 v32, v32
	v_mul_f32_e32 v35, v39, v36
	v_mul_f32_e32 v34, v35, v34
	v_cvt_pk_bf16_f32 v34, v34, s0
	v_mul_f32_e32 v35, 0x45800000, v32
	v_cndmask_b32_e32 v32, v32, v35, vcc
	v_mul_f32_e32 v35, v56, v32
	v_mul_f32_e32 v36, 0xbfb8aa3b, v35
	v_exp_f32_e32 v36, v36
	ds_write_b16 v84, v34 offset:1584
	v_cmp_gt_f32_e32 vcc, s62, v33
	v_mul_f32_e32 v32, v40, v32
	v_add_f32_e32 v34, 1.0, v36
	v_rcp_f32_e32 v34, v34
	v_mul_f32_e32 v36, 0x4b800000, v33
	v_cndmask_b32_e32 v33, v33, v36, vcc
	v_rsq_f32_e32 v33, v33
	v_mul_f32_e32 v34, v35, v34
	v_mul_f32_e32 v32, v32, v34
	v_cvt_pk_bf16_f32 v34, v32, s0
	v_mul_f32_e32 v32, 0x45800000, v33
	v_cndmask_b32_e32 v35, v33, v32, vcc
	v_mul_f32_e32 v36, v57, v35
	v_mul_f32_e32 v32, 0xbfb8aa3b, v36
	v_exp_f32_e32 v37, v32
	v_pk_fma_f32 v[32:33], v[66:67], s[8:9], v[82:83] op_sel_hi:[1,0,0]
	ds_write_b16 v84, v34 offset:2304
	v_mul_f32_e32 v38, 0x4b800000, v32
	v_cmp_gt_f32_e32 vcc, s62, v32
	v_add_f32_e32 v34, 1.0, v37
	v_rcp_f32_e32 v34, v34
	v_cndmask_b32_e32 v32, v32, v38, vcc
	v_rsq_f32_e32 v32, v32
	v_mul_f32_e32 v35, v41, v35
	v_mul_f32_e32 v34, v36, v34
	v_mul_f32_e32 v34, v35, v34
	v_mul_f32_e32 v37, 0x45800000, v32
	v_cndmask_b32_e32 v32, v32, v37, vcc
	v_mul_f32_e32 v37, v58, v32
	v_mul_f32_e32 v38, 0xbfb8aa3b, v37
	v_exp_f32_e32 v38, v38
	v_mul_f32_e32 v36, v42, v32
	v_mul_f32_e32 v32, 0x4b800000, v33
	v_cmp_gt_f32_e32 vcc, s62, v33
	v_add_f32_e32 v35, 1.0, v38
	v_rcp_f32_e32 v35, v35
	v_cndmask_b32_e32 v32, v33, v32, vcc
	v_rsq_f32_e32 v38, v32
	v_or_b32_e32 v32, 32, v86
	v_ashrrev_i32_e32 v33, 31, v32
	v_cvt_pk_bf16_f32 v34, v34, s0
	v_lshl_add_u64 v[32:33], v[32:33], 2, s[2:3]
	ds_write_b16 v84, v34 offset:2448
	v_mul_f32_e32 v37, v37, v35
	v_subrev_u32_e32 v167, s34, v32
	ds_read_b128 v[32:35], v167 offset:50176
	v_mul_f32_e32 v36, v36, v37
	v_mul_f32_e32 v37, 0x45800000, v38
	v_cndmask_b32_e32 v37, v38, v37, vcc
	v_mul_f32_e32 v38, v59, v37
	v_mul_f32_e32 v39, 0xbfb8aa3b, v38
	v_exp_f32_e32 v39, v39
	v_cvt_pk_bf16_f32 v36, v36, s0
	ds_write_b16 v84, v36 offset:2592
	v_mul_f32_e32 v40, v43, v37
	v_add_f32_e32 v36, 1.0, v39
	v_rcp_f32_e32 v39, v36
	s_waitcnt lgkmcnt(0)
	v_pk_fma_f32 v[36:37], v[48:49], s[8:9], v[82:83] op_sel_hi:[1,0,0]
	v_mul_f32_e32 v38, v38, v39
	v_mul_f32_e32 v41, 0x4b800000, v36
	v_cmp_gt_f32_e32 vcc, s62, v36
	v_mul_f32_e32 v38, v40, v38
	v_cvt_pk_bf16_f32 v38, v38, s0
	v_cndmask_b32_e32 v36, v36, v41, vcc
	v_rsq_f32_e32 v36, v36
	v_mul_f32_e32 v41, 0x4b800000, v37
	ds_write_b16 v84, v38 offset:2736
	v_mul_f32_e32 v39, 0x45800000, v36
	v_cndmask_b32_e32 v36, v36, v39, vcc
	v_mul_f32_e32 v39, v60, v36
	v_cmp_gt_f32_e32 vcc, s62, v37
	v_mul_f32_e32 v40, 0xbfb8aa3b, v39
	v_exp_f32_e32 v40, v40
	v_cndmask_b32_e32 v37, v37, v41, vcc
	v_rsq_f32_e32 v37, v37
	v_mul_f32_e32 v36, v44, v36
	v_add_f32_e32 v38, 1.0, v40
	v_rcp_f32_e32 v38, v38
	v_mul_f32_e32 v40, 0x45800000, v37
	v_cndmask_b32_e32 v37, v37, v40, vcc
	v_mul_f32_e32 v40, v61, v37
	v_mul_f32_e32 v41, 0xbfb8aa3b, v40
	v_exp_f32_e32 v41, v41
	v_mul_f32_e32 v38, v39, v38
	v_mul_f32_e32 v36, v36, v38
	v_cvt_pk_bf16_f32 v36, v36, s0
	v_add_f32_e32 v38, 1.0, v41
	v_rcp_f32_e32 v38, v38
	ds_write_b16 v84, v36 offset:3456
	v_mul_f32_e32 v39, v45, v37
	v_pk_fma_f32 v[36:37], v[50:51], s[8:9], v[82:83] op_sel_hi:[1,0,0]
	v_mul_f32_e32 v38, v40, v38
	v_mul_f32_e32 v40, 0x4b800000, v36
	v_cmp_gt_f32_e32 vcc, s62, v36
	v_mul_f32_e32 v38, v39, v38
	v_cvt_pk_bf16_f32 v38, v38, s0
	v_cndmask_b32_e32 v36, v36, v40, vcc
	v_rsq_f32_e32 v36, v36
	ds_write_b16 v84, v38 offset:3600
	v_mul_f32_e32 v39, 0x4b800000, v37
	v_mul_f32_e32 v38, 0x45800000, v36
	v_cndmask_b32_e32 v36, v36, v38, vcc
	v_mul_f32_e32 v40, v62, v36
	v_mul_f32_e32 v38, 0xbfb8aa3b, v40
	v_cmp_gt_f32_e32 vcc, s62, v37
	v_exp_f32_e32 v38, v38
	v_mul_f32_e32 v41, v46, v36
	v_cndmask_b32_e32 v37, v37, v39, vcc
	v_rsq_f32_e32 v37, v37
	v_add_f32_e32 v36, 1.0, v38
	v_rcp_f32_e32 v42, v36
	v_mul_f32_e32 v36, 0x45800000, v37
	v_cndmask_b32_e32 v43, v37, v36, vcc
	v_or_b32_e32 v36, 40, v86
	v_ashrrev_i32_e32 v37, 31, v36
	v_lshl_add_u64 v[36:37], v[36:37], 2, s[2:3]
	v_subrev_u32_e32 v167, s34, v36
	ds_read_b128 v[36:39], v167 offset:50176
	v_mul_f32_e32 v44, v63, v43
	v_mul_f32_e32 v40, v40, v42
	v_mul_f32_e32 v45, 0xbfb8aa3b, v44
	s_waitcnt lgkmcnt(0)
	v_pk_fma_f32 v[32:33], v[32:33], s[8:9], v[82:83] op_sel_hi:[1,0,0]
	v_exp_f32_e32 v45, v45
	v_mul_f32_e32 v42, 0x4b800000, v32
	v_cmp_gt_f32_e32 vcc, s62, v32
	v_mul_f32_e32 v40, v41, v40
	v_add_f32_e32 v41, 1.0, v45
	v_cndmask_b32_e32 v32, v32, v42, vcc
	v_rsq_f32_e32 v32, v32
	v_rcp_f32_e32 v41, v41
	v_cvt_pk_bf16_f32 v40, v40, s0
	ds_write_b16 v84, v40 offset:3744
	v_mul_f32_e32 v42, 0x45800000, v32
	v_cndmask_b32_e32 v32, v32, v42, vcc
	v_mul_f32_e32 v16, v16, v32
	v_mul_f32_e32 v42, 0xbfb8aa3b, v16
	v_exp_f32_e32 v42, v42
	v_mul_f32_e32 v40, v47, v43
	v_mul_f32_e32 v41, v44, v41
	v_mul_f32_e32 v40, v40, v41
	v_cvt_pk_bf16_f32 v40, v40, s0
	ds_write_b16 v84, v40 offset:3888
	v_add_f32_e32 v40, 1.0, v42
	v_mul_f32_e32 v41, 0x4b800000, v33
	v_cmp_gt_f32_e32 vcc, s62, v33
	v_rcp_f32_e32 v40, v40
	v_mul_f32_e32 v0, v0, v32
	v_cndmask_b32_e32 v33, v33, v41, vcc
	v_rsq_f32_e32 v33, v33
	v_mul_f32_e32 v16, v16, v40
	v_mul_f32_e32 v0, v0, v16
	v_cvt_pk_bf16_f32 v0, v0, s0
	v_mul_f32_e32 v16, 0x45800000, v33
	v_cndmask_b32_e32 v16, v33, v16, vcc
	v_mul_f32_e32 v17, v17, v16
	v_mul_f32_e32 v32, 0xbfb8aa3b, v17
	v_exp_f32_e32 v32, v32
	ds_write_b16 v84, v0 offset:4608
	v_mul_f32_e32 v16, v1, v16
	v_add_f32_e32 v0, 1.0, v32
	v_rcp_f32_e32 v32, v0
	v_pk_fma_f32 v[0:1], v[34:35], s[8:9], v[82:83] op_sel_hi:[1,0,0]
	v_mul_f32_e32 v17, v17, v32
	v_mul_f32_e32 v33, 0x4b800000, v0
	v_cmp_gt_f32_e32 vcc, s62, v0
	v_mul_f32_e32 v16, v16, v17
	v_cvt_pk_bf16_f32 v16, v16, s0
	v_cndmask_b32_e32 v0, v0, v33, vcc
	v_rsq_f32_e32 v0, v0
	ds_write_b16 v84, v16 offset:4752
	v_mul_f32_e32 v17, 0x45800000, v0
	v_cndmask_b32_e32 v32, v0, v17, vcc
	v_mul_f32_e32 v33, v18, v32
	v_mul_f32_e32 v0, 0xbfb8aa3b, v33
	v_mul_f32_e32 v17, 0x4b800000, v1
	v_cmp_gt_f32_e32 vcc, s62, v1
	v_exp_f32_e32 v0, v0
	s_nop 0
	v_cndmask_b32_e32 v1, v1, v17, vcc
	v_rsq_f32_e32 v1, v1
	v_add_f32_e32 v0, 1.0, v0
	v_rcp_f32_e32 v34, v0
	v_mul_f32_e32 v0, 0x45800000, v1
	v_cndmask_b32_e32 v35, v1, v0, vcc
	v_or_b32_e32 v0, 48, v86
	v_mul_f32_e32 v40, v19, v35
	v_ashrrev_i32_e32 v1, 31, v0
	v_mul_f32_e32 v41, 0xbfb8aa3b, v40
	v_lshl_add_u64 v[0:1], v[0:1], 2, s[2:3]
	v_subrev_u32_e32 v167, s34, v0
	ds_read_b128 v[16:19], v167 offset:50176
	v_exp_f32_e32 v0, v41
	v_mul_f32_e32 v1, v2, v32
	v_mul_f32_e32 v2, v33, v34
	v_mul_f32_e32 v1, v1, v2
	v_add_f32_e32 v0, 1.0, v0
	v_rcp_f32_e32 v0, v0
	v_cvt_pk_bf16_f32 v1, v1, s0
	ds_write_b16 v84, v1 offset:4896
	v_mul_f32_e32 v2, v3, v35
	v_mul_f32_e32 v3, v40, v0
	s_waitcnt lgkmcnt(0)
	v_pk_fma_f32 v[0:1], v[36:37], s[8:9], v[82:83] op_sel_hi:[1,0,0]
	v_mul_f32_e32 v2, v2, v3
	v_mul_f32_e32 v32, 0x4b800000, v0
	v_cmp_gt_f32_e32 vcc, s62, v0
	v_cvt_pk_bf16_f32 v2, v2, s0
	ds_write_b16 v84, v2 offset:5040
	v_cndmask_b32_e32 v0, v0, v32, vcc
	v_rsq_f32_e32 v0, v0
	s_nop 0
	v_mul_f32_e32 v2, 0x45800000, v0
	v_cndmask_b32_e32 v0, v0, v2, vcc
	v_mul_f32_e32 v2, v20, v0
	v_mul_f32_e32 v20, 0x4b800000, v1
	v_cmp_gt_f32_e32 vcc, s62, v1
	v_mul_f32_e32 v3, 0xbfb8aa3b, v2
	v_exp_f32_e32 v3, v3
	v_cndmask_b32_e32 v1, v1, v20, vcc
	v_rsq_f32_e32 v1, v1
	v_mul_f32_e32 v0, v4, v0
	v_add_f32_e32 v3, 1.0, v3
	v_rcp_f32_e32 v3, v3
	v_mul_f32_e32 v4, 0x45800000, v1
	v_cndmask_b32_e32 v1, v1, v4, vcc
	v_mul_f32_e32 v4, v21, v1
	v_mul_f32_e32 v20, 0xbfb8aa3b, v4
	v_exp_f32_e32 v20, v20
	v_mul_f32_e32 v2, v2, v3
	v_mul_f32_e32 v0, v0, v2
	v_cvt_pk_bf16_f32 v0, v0, s0
	v_add_f32_e32 v2, 1.0, v20
	v_pk_fma_f32 v[20:21], v[38:39], s[8:9], v[82:83] op_sel_hi:[1,0,0]
	v_rcp_f32_e32 v2, v2
	v_mul_f32_e32 v3, 0x4b800000, v20
	v_cmp_gt_f32_e32 vcc, s62, v20
	ds_write_b16 v84, v0 offset:5760
	v_mul_f32_e32 v0, v5, v1
	v_cndmask_b32_e32 v3, v20, v3, vcc
	v_rsq_f32_e32 v3, v3
	v_mul_f32_e32 v1, v4, v2
	v_mul_f32_e32 v0, v0, v1
	v_cvt_pk_bf16_f32 v0, v0, s0
	v_mul_f32_e32 v2, 0x45800000, v3
	v_cndmask_b32_e32 v4, v3, v2, vcc
	v_mul_f32_e32 v5, v22, v4
	v_mul_f32_e32 v2, 0xbfb8aa3b, v5
	v_exp_f32_e32 v2, v2
	ds_write_b16 v84, v0 offset:5904
	v_mul_f32_e32 v22, 0x4b800000, v21
	v_cmp_gt_f32_e32 vcc, s62, v21
	v_add_f32_e32 v0, 1.0, v2
	v_rcp_f32_e32 v20, v0
	v_or_b32_e32 v0, 56, v86
	v_ashrrev_i32_e32 v1, 31, v0
	v_lshl_add_u64 v[0:1], v[0:1], 2, s[2:3]
	v_subrev_u32_e32 v167, s34, v0
	ds_read_b128 v[0:3], v167 offset:50176
	v_cndmask_b32_e32 v21, v21, v22, vcc
	v_rsq_f32_e32 v21, v21
	v_mul_f32_e32 v4, v6, v4
	v_mul_f32_e32 v5, v5, v20
	v_mul_f32_e32 v4, v4, v5
	v_mul_f32_e32 v5, 0x45800000, v21
	v_cndmask_b32_e32 v5, v21, v5, vcc
	v_mul_f32_e32 v6, v23, v5
	v_mul_f32_e32 v20, 0xbfb8aa3b, v6
	v_exp_f32_e32 v20, v20
	v_cvt_pk_bf16_f32 v4, v4, s0
	ds_write_b16 v84, v4 offset:6048
	v_mul_f32_e32 v7, v7, v5
	v_add_f32_e32 v4, 1.0, v20
	v_rcp_f32_e32 v20, v4
	s_waitcnt lgkmcnt(0)
	v_pk_fma_f32 v[4:5], v[16:17], s[8:9], v[82:83] op_sel_hi:[1,0,0]
	v_mul_f32_e32 v6, v6, v20
	v_mul_f32_e32 v16, 0x4b800000, v4
	v_cmp_gt_f32_e32 vcc, s62, v4
	v_mul_f32_e32 v6, v7, v6
	v_mul_f32_e32 v17, 0x4b800000, v5
	v_cndmask_b32_e32 v4, v4, v16, vcc
	v_rsq_f32_e32 v4, v4
	v_cvt_pk_bf16_f32 v6, v6, s0
	ds_write_b16 v84, v6 offset:6192
	v_mul_f32_e32 v7, 0x45800000, v4
	v_cndmask_b32_e32 v4, v4, v7, vcc
	v_mul_f32_e32 v7, v24, v4
	v_cmp_gt_f32_e32 vcc, s62, v5
	v_mul_f32_e32 v16, 0xbfb8aa3b, v7
	v_exp_f32_e32 v16, v16
	v_cndmask_b32_e32 v5, v5, v17, vcc
	v_rsq_f32_e32 v5, v5
	v_mul_f32_e32 v4, v8, v4
	v_add_f32_e32 v6, 1.0, v16
	v_rcp_f32_e32 v6, v6
	v_mul_f32_e32 v16, 0x45800000, v5
	v_cndmask_b32_e32 v5, v5, v16, vcc
	v_mul_f32_e32 v16, v25, v5
	v_mul_f32_e32 v17, 0xbfb8aa3b, v16
	v_exp_f32_e32 v17, v17
	v_mul_f32_e32 v6, v7, v6
	v_mul_f32_e32 v4, v4, v6
	v_cvt_pk_bf16_f32 v4, v4, s0
	v_add_f32_e32 v6, 1.0, v17
	v_rcp_f32_e32 v6, v6
	ds_write_b16 v84, v4 offset:6912
	v_mul_f32_e32 v7, v9, v5
	v_pk_fma_f32 v[4:5], v[18:19], s[8:9], v[82:83] op_sel_hi:[1,0,0]
	v_mul_f32_e32 v6, v16, v6
	v_mul_f32_e32 v8, 0x4b800000, v4
	v_cmp_gt_f32_e32 vcc, s62, v4
	v_mul_f32_e32 v6, v7, v6
	v_cvt_pk_bf16_f32 v6, v6, s0
	v_cndmask_b32_e32 v4, v4, v8, vcc
	v_rsq_f32_e32 v4, v4
	ds_write_b16 v84, v6 offset:7056
	v_mul_f32_e32 v8, 0x4b800000, v5
	v_mul_f32_e32 v6, 0x45800000, v4
	v_cndmask_b32_e32 v4, v4, v6, vcc
	v_cmp_gt_f32_e32 vcc, s62, v5
	v_mul_f32_e32 v6, v26, v4
	v_mul_f32_e32 v7, 0xbfb8aa3b, v6
	v_cndmask_b32_e32 v5, v5, v8, vcc
	v_rsq_f32_e32 v5, v5
	v_exp_f32_e32 v7, v7
	v_mul_f32_e32 v4, v10, v4
	v_mul_f32_e32 v8, 0x45800000, v5
	v_cndmask_b32_e32 v5, v5, v8, vcc
	v_add_f32_e32 v7, 1.0, v7
	v_mul_f32_e32 v8, v27, v5
	v_rcp_f32_e32 v7, v7
	v_mul_f32_e32 v9, 0xbfb8aa3b, v8
	v_exp_f32_e32 v9, v9
	s_waitcnt lgkmcnt(0)
	v_pk_fma_f32 v[0:1], v[0:1], s[8:9], v[82:83] op_sel_hi:[1,0,0]
	v_mul_f32_e32 v6, v6, v7
	v_mul_f32_e32 v7, 0x4b800000, v0
	v_cmp_gt_f32_e32 vcc, s62, v0
	v_mul_f32_e32 v4, v4, v6
	v_add_f32_e32 v6, 1.0, v9
	v_cndmask_b32_e32 v0, v0, v7, vcc
	v_rcp_f32_e32 v6, v6
	v_rsq_f32_e32 v0, v0
	v_cvt_pk_bf16_f32 v4, v4, s0
	ds_write_b16 v84, v4 offset:7200
	v_mul_f32_e32 v4, v11, v5
	v_mul_f32_e32 v5, v8, v6
	v_mul_f32_e32 v6, 0x45800000, v0
	v_cndmask_b32_e32 v0, v0, v6, vcc
	v_mul_f32_e32 v6, v28, v0
	v_mul_f32_e32 v7, 0xbfb8aa3b, v6
	v_exp_f32_e32 v7, v7
	v_mul_f32_e32 v4, v4, v5
	v_cvt_pk_bf16_f32 v4, v4, s0
	ds_write_b16 v84, v4 offset:7344
	v_add_f32_e32 v4, 1.0, v7
	v_mul_f32_e32 v5, 0x4b800000, v1
	v_cmp_gt_f32_e32 vcc, s62, v1
	v_rcp_f32_e32 v4, v4
	v_mul_f32_e32 v0, v12, v0
	v_cndmask_b32_e32 v1, v1, v5, vcc
	v_rsq_f32_e32 v1, v1
	v_mul_f32_e32 v4, v6, v4
	v_mul_f32_e32 v0, v0, v4
	v_cvt_pk_bf16_f32 v0, v0, s0
	v_mul_f32_e32 v4, 0x45800000, v1
	v_cndmask_b32_e32 v1, v1, v4, vcc
	v_mul_f32_e32 v4, v29, v1
	v_mul_f32_e32 v5, 0xbfb8aa3b, v4
	v_exp_f32_e32 v5, v5
	ds_write_b16 v84, v0 offset:8064
	v_mul_f32_e32 v6, v13, v1
	v_add_f32_e32 v0, 1.0, v5
	v_rcp_f32_e32 v5, v0
	v_pk_fma_f32 v[0:1], v[2:3], s[8:9], v[82:83] op_sel_hi:[1,0,0]
	v_mul_f32_e32 v2, 0x4b800000, v0
	v_cmp_gt_f32_e32 vcc, s62, v0
	s_nop 0
	v_cndmask_b32_e32 v0, v0, v2, vcc
	v_rsq_f32_e32 v0, v0
	v_mul_f32_e32 v2, v4, v5
	v_mul_f32_e32 v5, 0x4b800000, v1
	v_mul_f32_e32 v2, v6, v2
	v_mul_f32_e32 v3, 0x45800000, v0
	v_cndmask_b32_e32 v0, v0, v3, vcc
	v_mul_f32_e32 v3, v30, v0
	v_cmp_gt_f32_e32 vcc, s62, v1
	v_mul_f32_e32 v4, 0xbfb8aa3b, v3
	v_exp_f32_e32 v4, v4
	v_cndmask_b32_e32 v1, v1, v5, vcc
	v_rsq_f32_e32 v1, v1
	v_cvt_pk_bf16_f32 v2, v2, s0
	ds_write_b16 v84, v2 offset:8208
	v_add_f32_e32 v2, 1.0, v4
	v_mul_f32_e32 v4, 0x45800000, v1
	v_cndmask_b32_e32 v1, v1, v4, vcc
	v_mul_f32_e32 v4, v31, v1
	v_rcp_f32_e32 v2, v2
	v_mul_f32_e32 v5, 0xbfb8aa3b, v4
	v_exp_f32_e32 v5, v5
	v_mul_f32_e32 v0, v14, v0
	v_mul_f32_e32 v2, v3, v2
	v_mul_f32_e32 v0, v0, v2
	v_add_f32_e32 v2, 1.0, v5
	v_rcp_f32_e32 v2, v2
	v_cvt_pk_bf16_f32 v0, v0, s0
	ds_write_b16 v84, v0 offset:8352
	v_mul_f32_e32 v0, v15, v1
	v_mul_f32_e32 v1, v4, v2
	v_mul_f32_e32 v0, v0, v1
	v_cvt_pk_bf16_f32 v0, v0, s0
	ds_write_b16 v84, v0 offset:8496
	v_lshlrev_b32_e32 v0, 3, v81
	v_ashrrev_i32_e32 v6, 3, v81
	v_and_b32_e32 v0, 56, v0
	v_add_u32_e32 v4, s15, v6
	v_lshlrev_b32_e32 v8, 1, v0
	v_lshl_or_b32 v0, s14, 6, v0
	v_ashrrev_i32_e32 v4, 7, v4
	v_ashrrev_i32_e32 v10, 5, v0
	v_mul_lo_u32 v4, v4, s63
	v_ashrrev_i32_e32 v11, 31, v10
	v_ashrrev_i32_e32 v5, 31, v4
	v_lshl_add_u64 v[4:5], v[4:5], 0, v[10:11]
	v_mad_u64_u32 v[0:1], s[0:1], v6, s61, v[8:9]
	v_lshlrev_b64 v[4:5], 13, v[4:5]
	v_lshlrev_b32_e32 v6, 6, v6
	s_waitcnt lgkmcnt(0)
	s_barrier
	ds_read_b128 v[0:3], v0
	v_lshl_add_u64 v[4:5], s[46:47], 0, v[4:5]
	v_and_b32_e32 v72, 0x1fc0, v6
	v_lshlrev_b32_e32 v6, 4, v81
	v_lshl_add_u64 v[4:5], v[4:5], 0, v[72:73]
	v_and_b32_e32 v72, 48, v6
	v_lshl_add_u64 v[12:13], v[4:5], 0, v[72:73]
	v_add_u32_e32 v4, 0x100, v81
	v_ashrrev_i32_e32 v9, 3, v4
	v_mad_u64_u32 v[4:5], s[0:1], v9, s61, v[8:9]
	ds_read_b128 v[4:7], v4
	s_waitcnt lgkmcnt(1)
	global_store_dwordx4 v[12:13], v[0:3], off
	s_nop 1
	v_add_u32_e32 v0, s15, v9
	v_ashrrev_i32_e32 v0, 7, v0
	v_mul_lo_u32 v0, v0, s63
	v_ashrrev_i32_e32 v1, 31, v0
	v_lshl_add_u64 v[0:1], v[0:1], 0, v[10:11]
	v_lshlrev_b64 v[0:1], 13, v[0:1]
	v_lshlrev_b32_e32 v2, 6, v9
	v_lshl_add_u64 v[0:1], s[46:47], 0, v[0:1]
	v_and_b32_e32 v2, 0x1fc0, v2
	v_mov_b32_e32 v3, v73
	v_lshl_add_u64 v[0:1], v[0:1], 0, v[2:3]
	v_lshl_add_u64 v[0:1], v[0:1], 0, v[72:73]
	s_waitcnt lgkmcnt(0)
	global_store_dwordx4 v[0:1], v[4:7], off
	v_add_u32_e32 v0, 0x200, v81
	s_nop 0
	v_ashrrev_i32_e32 v6, 3, v0
	v_add_u32_e32 v4, s15, v6
	v_ashrrev_i32_e32 v4, 7, v4
	v_mul_lo_u32 v4, v4, s63
	v_ashrrev_i32_e32 v5, 31, v4
	v_lshl_add_u64 v[4:5], v[4:5], 0, v[10:11]
	v_mad_u64_u32 v[0:1], s[0:1], v6, s61, v[8:9]
	v_lshlrev_b64 v[4:5], 13, v[4:5]
	v_lshlrev_b32_e32 v6, 6, v6
	ds_read_b128 v[0:3], v0
	v_lshl_add_u64 v[4:5], s[46:47], 0, v[4:5]
	v_and_b32_e32 v6, 0x1fc0, v6
	v_mov_b32_e32 v7, v73
	v_lshl_add_u64 v[4:5], v[4:5], 0, v[6:7]
	v_lshl_add_u64 v[12:13], v[4:5], 0, v[72:73]
	v_add_u32_e32 v4, 0x300, v81
	v_ashrrev_i32_e32 v9, 3, v4
	v_mad_u64_u32 v[4:5], s[0:1], v9, s61, v[8:9]
	ds_read_b128 v[4:7], v4
	s_waitcnt lgkmcnt(1)
	global_store_dwordx4 v[12:13], v[0:3], off
	s_nop 1
	v_add_u32_e32 v0, s15, v9
	v_ashrrev_i32_e32 v0, 7, v0
	v_mul_lo_u32 v0, v0, s63
	v_ashrrev_i32_e32 v1, 31, v0
	v_lshl_add_u64 v[0:1], v[0:1], 0, v[10:11]
	v_lshlrev_b64 v[0:1], 13, v[0:1]
	v_lshlrev_b32_e32 v2, 6, v9
	v_lshl_add_u64 v[0:1], s[46:47], 0, v[0:1]
	v_and_b32_e32 v2, 0x1fc0, v2
	v_mov_b32_e32 v3, v73
	v_lshl_add_u64 v[0:1], v[0:1], 0, v[2:3]
	v_lshl_add_u64 v[0:1], v[0:1], 0, v[72:73]
	s_waitcnt lgkmcnt(0)
	global_store_dwordx4 v[0:1], v[4:7], off

	.amdhsa_kernel _Z6k_mega6Params
		.amdhsa_group_segment_fixed_size 51200
		.amdhsa_private_segment_fixed_size 0
		.amdhsa_kernarg_size 616
		.amdhsa_user_sgpr_count 2
		.amdhsa_user_sgpr_dispatch_ptr 0
		.amdhsa_user_sgpr_queue_ptr 0
		.amdhsa_user_sgpr_kernarg_segment_ptr 1
		.amdhsa_user_sgpr_dispatch_id 0
		.amdhsa_user_sgpr_kernarg_preload_length 0
		.amdhsa_user_sgpr_kernarg_preload_offset 0
		.amdhsa_user_sgpr_private_segment_size 0
		.amdhsa_uses_dynamic_stack 0
		.amdhsa_enable_private_segment 0
		.amdhsa_system_sgpr_workgroup_id_x 1
		.amdhsa_system_sgpr_workgroup_id_y 0
		.amdhsa_system_sgpr_workgroup_id_z 0
		.amdhsa_system_sgpr_workgroup_info 0
		.amdhsa_system_vgpr_workitem_id 2
		.amdhsa_next_free_vgpr 168
		.amdhsa_next_free_sgpr 98
		.amdhsa_accum_offset 168
		.amdhsa_reserve_vcc 1
		.amdhsa_float_round_mode_32 0
		.amdhsa_float_round_mode_16_64 0
		.amdhsa_float_denorm_mode_32 3
		.amdhsa_float_denorm_mode_16_64 3
		.amdhsa_dx10_clamp 1
		.amdhsa_ieee_mode 1
		.amdhsa_fp16_overflow 0
		.amdhsa_tg_split 0
		.amdhsa_exception_fp_ieee_invalid_op 0
		.amdhsa_exception_fp_denorm_src 0
		.amdhsa_exception_fp_ieee_div_zero 0
		.amdhsa_exception_fp_ieee_overflow 0
		.amdhsa_exception_fp_ieee_underflow 0
		.amdhsa_exception_fp_ieee_inexact 0
		.amdhsa_exception_int_div_zero 0
	.end_amdhsa_kernel

amdhsa.kernels:
  - .agpr_count:     0
    .args:
      - .offset:         0
        .size:           360
        .value_kind:     by_value
      - .offset:         360
        .size:           4
        .value_kind:     hidden_block_count_x
      - .offset:         364
        .size:           4
        .value_kind:     hidden_block_count_y
      - .offset:         368
        .size:           4
        .value_kind:     hidden_block_count_z
      - .offset:         372
        .size:           2
        .value_kind:     hidden_group_size_x
      - .offset:         374
        .size:           2
        .value_kind:     hidden_group_size_y
      - .offset:         376
        .size:           2
        .value_kind:     hidden_group_size_z
      - .offset:         378
        .size:           2
        .value_kind:     hidden_remainder_x
      - .offset:         380
        .size:           2
        .value_kind:     hidden_remainder_y
      - .offset:         382
        .size:           2
        .value_kind:     hidden_remainder_z
      - .offset:         400
        .size:           8
        .value_kind:     hidden_global_offset_x
      - .offset:         408
        .size:           8
        .value_kind:     hidden_global_offset_y
      - .offset:         416
        .size:           8
        .value_kind:     hidden_global_offset_z
      - .offset:         424
        .size:           2
        .value_kind:     hidden_grid_dims
      - .offset:         448
        .size:           8
        .value_kind:     hidden_multigrid_sync_arg
    .group_segment_fixed_size: 51200
    .kernarg_segment_align: 8
    .kernarg_segment_size: 616
    .language:       OpenCL C
    .language_version:
      - 2
      - 0
    .max_flat_workgroup_size: 256
    .name:           _Z6k_mega6Params
    .private_segment_fixed_size: 0
    .sgpr_count:     104
    .sgpr_spill_count: 130
    .symbol:         _Z6k_mega6Params.kd
    .uniform_work_group_size: 1
    .uses_dynamic_stack: false
    .vgpr_count:     168
    .vgpr_spill_count: 0
    .wavefront_size: 64
